# delta_pre: forward substitution done in registers (lane per column, L rows broadcast-read via prefetch ring) instead of 63 LDS round-trip steps
# speedup vs baseline: 1.1257x; 1.0209x over previous
.LBB0_413:
	s_or_b64 exec, exec, s[12:13]
	v_lshlrev_b32_e32 v4, 2, v245
	ds_read2st64_b32 v[32:33], v4 offset0:200 offset1:202
	ds_read_b128 v[4:7], v126 offset:17408
	ds_read_b128 v[12:15], v126 offset:17424
	ds_read_b128 v[16:19], v126 offset:17440
	ds_read_b128 v[24:27], v126 offset:17456
	s_waitcnt lgkmcnt(4)
	v_mul_f32_e32 v28, 0x3fb8aa3b, v33
	v_exp_f32_e32 v33, v28
	s_movk_i32 s2, 0x80
	v_cmp_gt_i32_e32 vcc, s2, v204
	s_mov_b32 s5, 1
	v_pk_mul_f32 v[28:29], v[84:85], v[32:33] op_sel_hi:[1,0]
	v_pk_mul_f32 v[30:31], v[72:73], v[32:33] op_sel_hi:[1,0]
	ds_write_b128 v126, v[28:31]
	v_mul_f32_e32 v28, v32, v33
	s_waitcnt lgkmcnt(4)
	v_pk_mul_f32 v[4:5], v[4:5], v[28:29] op_sel_hi:[1,0]
	v_pk_mul_f32 v[6:7], v[28:29], v[6:7] op_sel_hi:[0,1]
	ds_write_b128 v126, v[4:7] offset:17408
	v_pk_mul_f32 v[4:5], v[20:21], v[32:33] op_sel_hi:[1,0]
	v_pk_mul_f32 v[6:7], v[22:23], v[32:33] op_sel_hi:[1,0]
	ds_write_b128 v126, v[4:7] offset:16
	v_pk_mul_f32 v[4:5], v[8:9], v[32:33] op_sel_hi:[1,0]
	v_pk_mul_f32 v[6:7], v[10:11], v[32:33] op_sel_hi:[1,0]
	ds_write_b128 v126, v[4:7] offset:32
	v_pk_mul_f32 v[0:1], v[0:1], v[32:33] op_sel_hi:[1,0]
	s_waitcnt lgkmcnt(4)
	v_pk_mul_f32 v[4:5], v[28:29], v[24:25] op_sel_hi:[0,1]
	v_pk_mul_f32 v[2:3], v[2:3], v[32:33] op_sel_hi:[1,0]
	v_pk_mul_f32 v[6:7], v[28:29], v[26:27] op_sel_hi:[0,1]
	ds_write_b128 v126, v[0:3] offset:48
	ds_write_b128 v126, v[4:7] offset:17456
	v_and_b32_e32 v4, 1, v204
	v_lshlrev_b32_e32 v1, 1, v204
	v_cndmask_b32_e64 v3, v239, 0, vcc
	v_lshlrev_b32_e32 v0, 2, v4
	v_and_b32_e32 v5, 0xfc, v1
	v_cmp_eq_u32_e32 vcc, 0, v4
	v_lshl_or_b32 v2, v4, 4, v241
	v_mul_u32_u24_e32 v4, 0x440, v4
	v_pk_mul_f32 v[12:13], v[28:29], v[12:13] op_sel_hi:[0,1]
	v_pk_mul_f32 v[14:15], v[28:29], v[14:15] op_sel_hi:[0,1]
	v_pk_mul_f32 v[8:9], v[28:29], v[16:17] op_sel_hi:[0,1]
	v_pk_mul_f32 v[10:11], v[28:29], v[18:19] op_sel_hi:[0,1]
	v_or_b32_e32 v1, v3, v5
	v_add3_u32 v3, v4, v5, v3
	ds_write_b128 v126, v[12:15] offset:17424
	ds_write_b128 v126, v[8:11] offset:17440
	s_waitcnt lgkmcnt(0)
	s_barrier
	v_readfirstlane_b32 s2, v216
	s_nop 0
	s_cmp_ge_u32 s2, 0x80
	s_cbranch_scc1 .Ldp_fs_end
	s_lshr_b32 s3, s2, 6
	s_mulk_i32 s3, 0x4400
	v_and_b32_e32 v72, 63, v216
	v_lshlrev_b32_e32 v72, 2, v72
	v_add_u32_e32 v72, s3, v72
	ds_read_b32 v0, v72 offset:0
	ds_read_b32 v1, v72 offset:272
	ds_read_b32 v2, v72 offset:544
	ds_read_b32 v3, v72 offset:816
	ds_read_b32 v4, v72 offset:1088
	ds_read_b32 v5, v72 offset:1360
	ds_read_b32 v6, v72 offset:1632
	ds_read_b32 v7, v72 offset:1904
	ds_read_b32 v8, v72 offset:2176
	ds_read_b32 v9, v72 offset:2448
	s_waitcnt lgkmcnt(4)
	ds_read_b32 v10, v72 offset:2720
	ds_read_b32 v11, v72 offset:2992
	ds_read_b32 v12, v72 offset:3264
	ds_read_b32 v13, v72 offset:3536
	ds_read_b32 v14, v72 offset:3808
	ds_read_b32 v15, v72 offset:4080
	ds_read_b32 v16, v72 offset:4352
	ds_read_b32 v17, v72 offset:4624
	ds_read_b32 v18, v72 offset:4896
	ds_read_b32 v19, v72 offset:5168
	s_waitcnt lgkmcnt(4)
	ds_read_b32 v20, v72 offset:5440
	ds_read_b32 v21, v72 offset:5712
	ds_read_b32 v22, v72 offset:5984
	ds_read_b32 v23, v72 offset:6256
	ds_read_b32 v24, v72 offset:6528
	ds_read_b32 v25, v72 offset:6800
	ds_read_b32 v26, v72 offset:7072
	ds_read_b32 v27, v72 offset:7344
	ds_read_b32 v28, v72 offset:7616
	ds_read_b32 v29, v72 offset:7888
	s_waitcnt lgkmcnt(4)
	ds_read_b32 v30, v72 offset:8160
	ds_read_b32 v31, v72 offset:8432
	ds_read_b32 v32, v72 offset:8704
	ds_read_b32 v33, v72 offset:8976
	ds_read_b32 v34, v72 offset:9248
	ds_read_b32 v35, v72 offset:9520
	ds_read_b32 v36, v72 offset:9792
	ds_read_b32 v37, v72 offset:10064
	ds_read_b32 v38, v72 offset:10336
	ds_read_b32 v39, v72 offset:10608
	s_waitcnt lgkmcnt(4)
	ds_read_b32 v40, v72 offset:10880
	ds_read_b32 v41, v72 offset:11152
	ds_read_b32 v42, v72 offset:11424
	ds_read_b32 v43, v72 offset:11696
	ds_read_b32 v44, v72 offset:11968
	ds_read_b32 v45, v72 offset:12240
	ds_read_b32 v46, v72 offset:12512
	ds_read_b32 v47, v72 offset:12784
	ds_read_b32 v48, v72 offset:13056
	ds_read_b32 v49, v72 offset:13328
	s_waitcnt lgkmcnt(4)
	ds_read_b32 v50, v72 offset:13600
	ds_read_b32 v51, v72 offset:13872
	ds_read_b32 v52, v72 offset:14144
	ds_read_b32 v53, v72 offset:14416
	ds_read_b32 v54, v72 offset:14688
	ds_read_b32 v55, v72 offset:14960
	ds_read_b32 v56, v72 offset:15232
	ds_read_b32 v57, v72 offset:15504
	ds_read_b32 v58, v72 offset:15776
	ds_read_b32 v59, v72 offset:16048
	s_waitcnt lgkmcnt(4)
	ds_read_b32 v60, v72 offset:16320
	ds_read_b32 v61, v72 offset:16592
	ds_read_b32 v62, v72 offset:16864
	ds_read_b32 v63, v72 offset:17136
	s_waitcnt lgkmcnt(0)
	ds_read_b128 v[96:99], v201 offset:35072
	ds_read_b128 v[100:103], v201 offset:35328
	ds_read_b128 v[104:107], v201 offset:35584
	ds_read_b128 v[108:111], v201 offset:35840
	ds_read_b128 v[112:115], v201 offset:36096
	ds_read_b128 v[116:119], v201 offset:36112
	ds_read_b128 v[120:123], v201 offset:36352
	ds_read_b128 v[124:127], v201 offset:36368
	ds_read_b128 v[128:131], v201 offset:36608
	ds_read_b128 v[132:135], v201 offset:36624
	ds_read_b128 v[136:139], v201 offset:36864
	ds_read_b128 v[140:143], v201 offset:36880
	ds_read_b128 v[144:147], v201 offset:37120
	s_waitcnt lgkmcnt(12)
	v_pk_mul_f32 v[64:65], v[96:97], v[0:1]
	v_pk_mul_f32 v[66:67], v[98:99], v[2:3]
	s_nop 0
	v_pk_add_f32 v[68:69], v[64:65], v[66:67]
	s_nop 0
	v_add_f32_e32 v70, v68, v69
	v_sub_f32_e32 v1, v1, v70
	ds_read_b128 v[148:151], v201 offset:37136
	s_waitcnt lgkmcnt(12)
	v_pk_mul_f32 v[64:65], v[100:101], v[0:1]
	v_pk_mul_f32 v[66:67], v[102:103], v[2:3]
	s_nop 0
	v_pk_add_f32 v[68:69], v[64:65], v[66:67]
	s_nop 0
	v_add_f32_e32 v70, v68, v69
	v_sub_f32_e32 v2, v2, v70
	ds_read_b128 v[152:155], v201 offset:37152
	s_waitcnt lgkmcnt(12)
	v_pk_mul_f32 v[64:65], v[104:105], v[0:1]
	v_pk_mul_f32 v[66:67], v[106:107], v[2:3]
	s_nop 0
	v_pk_add_f32 v[68:69], v[64:65], v[66:67]
	s_nop 0
	v_add_f32_e32 v70, v68, v69
	v_sub_f32_e32 v3, v3, v70
	ds_read_b128 v[156:159], v201 offset:37376
	s_waitcnt lgkmcnt(12)
	v_pk_mul_f32 v[64:65], v[108:109], v[0:1]
	v_pk_mul_f32 v[66:67], v[110:111], v[2:3]
	s_nop 0
	v_pk_add_f32 v[68:69], v[64:65], v[66:67]
	s_nop 0
	v_add_f32_e32 v70, v68, v69
	v_sub_f32_e32 v4, v4, v70
	ds_read_b128 v[96:99], v201 offset:37392
	s_waitcnt lgkmcnt(12)
	v_pk_mul_f32 v[64:65], v[112:113], v[0:1]
	v_pk_mul_f32 v[66:67], v[114:115], v[2:3]
	ds_read_b128 v[100:103], v201 offset:37408
	s_waitcnt lgkmcnt(12)
	v_pk_fma_f32 v[64:65], v[116:117], v[4:5], v[64:65]
	v_pk_fma_f32 v[66:67], v[118:119], v[6:7], v[66:67]
	s_nop 0
	v_pk_add_f32 v[68:69], v[64:65], v[66:67]
	s_nop 0
	v_add_f32_e32 v70, v68, v69
	v_sub_f32_e32 v5, v5, v70
	ds_read_b128 v[104:107], v201 offset:37632
	s_waitcnt lgkmcnt(12)
	v_pk_mul_f32 v[64:65], v[120:121], v[0:1]
	v_pk_mul_f32 v[66:67], v[122:123], v[2:3]
	ds_read_b128 v[108:111], v201 offset:37648
	s_waitcnt lgkmcnt(12)
	v_pk_fma_f32 v[64:65], v[124:125], v[4:5], v[64:65]
	v_pk_fma_f32 v[66:67], v[126:127], v[6:7], v[66:67]
	s_nop 0
	v_pk_add_f32 v[68:69], v[64:65], v[66:67]
	s_nop 0
	v_add_f32_e32 v70, v68, v69
	v_sub_f32_e32 v6, v6, v70
	ds_read_b128 v[112:115], v201 offset:37664
	s_waitcnt lgkmcnt(12)
	v_pk_mul_f32 v[64:65], v[128:129], v[0:1]
	v_pk_mul_f32 v[66:67], v[130:131], v[2:3]
	ds_read_b128 v[116:119], v201 offset:37888
	s_waitcnt lgkmcnt(12)
	v_pk_fma_f32 v[64:65], v[132:133], v[4:5], v[64:65]
	v_pk_fma_f32 v[66:67], v[134:135], v[6:7], v[66:67]
	s_nop 0
	v_pk_add_f32 v[68:69], v[64:65], v[66:67]
	s_nop 0
	v_add_f32_e32 v70, v68, v69
	v_sub_f32_e32 v7, v7, v70
	ds_read_b128 v[120:123], v201 offset:37904
	s_waitcnt lgkmcnt(12)
	v_pk_mul_f32 v[64:65], v[136:137], v[0:1]
	v_pk_mul_f32 v[66:67], v[138:139], v[2:3]
	ds_read_b128 v[124:127], v201 offset:37920
	s_waitcnt lgkmcnt(12)
	v_pk_fma_f32 v[64:65], v[140:141], v[4:5], v[64:65]
	v_pk_fma_f32 v[66:67], v[142:143], v[6:7], v[66:67]
	s_nop 0
	v_pk_add_f32 v[68:69], v[64:65], v[66:67]
	s_nop 0
	v_add_f32_e32 v70, v68, v69
	v_sub_f32_e32 v8, v8, v70
	ds_read_b128 v[128:131], v201 offset:38144
	s_waitcnt lgkmcnt(12)
	v_pk_mul_f32 v[64:65], v[144:145], v[0:1]
	v_pk_mul_f32 v[66:67], v[146:147], v[2:3]
	ds_read_b128 v[132:135], v201 offset:38160
	s_waitcnt lgkmcnt(12)
	v_pk_fma_f32 v[64:65], v[148:149], v[4:5], v[64:65]
	v_pk_fma_f32 v[66:67], v[150:151], v[6:7], v[66:67]
	ds_read_b128 v[136:139], v201 offset:38176
	s_waitcnt lgkmcnt(12)
	v_pk_fma_f32 v[64:65], v[152:153], v[8:9], v[64:65]
	v_pk_fma_f32 v[66:67], v[154:155], v[10:11], v[66:67]
	s_nop 0
	v_pk_add_f32 v[68:69], v[64:65], v[66:67]
	s_nop 0
	v_add_f32_e32 v70, v68, v69
	v_sub_f32_e32 v9, v9, v70
	ds_read_b128 v[140:143], v201 offset:38192
	s_waitcnt lgkmcnt(12)
	v_pk_mul_f32 v[64:65], v[156:157], v[0:1]
	v_pk_mul_f32 v[66:67], v[158:159], v[2:3]
	ds_read_b128 v[144:147], v201 offset:38400
	s_waitcnt lgkmcnt(12)
	v_pk_fma_f32 v[64:65], v[96:97], v[4:5], v[64:65]
	v_pk_fma_f32 v[66:67], v[98:99], v[6:7], v[66:67]
	ds_read_b128 v[148:151], v201 offset:38416
	s_waitcnt lgkmcnt(12)
	v_pk_fma_f32 v[64:65], v[100:101], v[8:9], v[64:65]
	v_pk_fma_f32 v[66:67], v[102:103], v[10:11], v[66:67]
	s_nop 0
	v_pk_add_f32 v[68:69], v[64:65], v[66:67]
	s_nop 0
	v_add_f32_e32 v70, v68, v69
	v_sub_f32_e32 v10, v10, v70
	ds_read_b128 v[152:155], v201 offset:38432
	s_waitcnt lgkmcnt(12)
	v_pk_mul_f32 v[64:65], v[104:105], v[0:1]
	v_pk_mul_f32 v[66:67], v[106:107], v[2:3]
	ds_read_b128 v[156:159], v201 offset:38448
	s_waitcnt lgkmcnt(12)
	v_pk_fma_f32 v[64:65], v[108:109], v[4:5], v[64:65]
	v_pk_fma_f32 v[66:67], v[110:111], v[6:7], v[66:67]
	ds_read_b128 v[96:99], v201 offset:38656
	s_waitcnt lgkmcnt(12)
	v_pk_fma_f32 v[64:65], v[112:113], v[8:9], v[64:65]
	v_pk_fma_f32 v[66:67], v[114:115], v[10:11], v[66:67]
	s_nop 0
	v_pk_add_f32 v[68:69], v[64:65], v[66:67]
	s_nop 0
	v_add_f32_e32 v70, v68, v69
	v_sub_f32_e32 v11, v11, v70
	ds_read_b128 v[100:103], v201 offset:38672
	s_waitcnt lgkmcnt(12)
	v_pk_mul_f32 v[64:65], v[116:117], v[0:1]
	v_pk_mul_f32 v[66:67], v[118:119], v[2:3]
	ds_read_b128 v[104:107], v201 offset:38688
	s_waitcnt lgkmcnt(12)
	v_pk_fma_f32 v[64:65], v[120:121], v[4:5], v[64:65]
	v_pk_fma_f32 v[66:67], v[122:123], v[6:7], v[66:67]
	ds_read_b128 v[108:111], v201 offset:38704
	s_waitcnt lgkmcnt(12)
	v_pk_fma_f32 v[64:65], v[124:125], v[8:9], v[64:65]
	v_pk_fma_f32 v[66:67], v[126:127], v[10:11], v[66:67]
	s_nop 0
	v_pk_add_f32 v[68:69], v[64:65], v[66:67]
	s_nop 0
	v_add_f32_e32 v70, v68, v69
	v_sub_f32_e32 v12, v12, v70
	ds_read_b128 v[112:115], v201 offset:38912
	s_waitcnt lgkmcnt(12)
	v_pk_mul_f32 v[64:65], v[128:129], v[0:1]
	v_pk_mul_f32 v[66:67], v[130:131], v[2:3]
	ds_read_b128 v[116:119], v201 offset:38928
	s_waitcnt lgkmcnt(12)
	v_pk_fma_f32 v[64:65], v[132:133], v[4:5], v[64:65]
	v_pk_fma_f32 v[66:67], v[134:135], v[6:7], v[66:67]
	ds_read_b128 v[120:123], v201 offset:38944
	s_waitcnt lgkmcnt(12)
	v_pk_fma_f32 v[64:65], v[136:137], v[8:9], v[64:65]
	v_pk_fma_f32 v[66:67], v[138:139], v[10:11], v[66:67]
	ds_read_b128 v[124:127], v201 offset:38960
	s_waitcnt lgkmcnt(12)
	v_pk_fma_f32 v[64:65], v[140:141], v[12:13], v[64:65]
	v_pk_fma_f32 v[66:67], v[142:143], v[14:15], v[66:67]
	s_nop 0
	v_pk_add_f32 v[68:69], v[64:65], v[66:67]
	s_nop 0
	v_add_f32_e32 v70, v68, v69
	v_sub_f32_e32 v13, v13, v70
	ds_read_b128 v[128:131], v201 offset:39168
	s_waitcnt lgkmcnt(12)
	v_pk_mul_f32 v[64:65], v[144:145], v[0:1]
	v_pk_mul_f32 v[66:67], v[146:147], v[2:3]
	ds_read_b128 v[132:135], v201 offset:39184
	s_waitcnt lgkmcnt(12)
	v_pk_fma_f32 v[64:65], v[148:149], v[4:5], v[64:65]
	v_pk_fma_f32 v[66:67], v[150:151], v[6:7], v[66:67]
	ds_read_b128 v[136:139], v201 offset:39200
	s_waitcnt lgkmcnt(12)
	v_pk_fma_f32 v[64:65], v[152:153], v[8:9], v[64:65]
	v_pk_fma_f32 v[66:67], v[154:155], v[10:11], v[66:67]
	ds_read_b128 v[140:143], v201 offset:39216
	s_waitcnt lgkmcnt(12)
	v_pk_fma_f32 v[64:65], v[156:157], v[12:13], v[64:65]
	v_pk_fma_f32 v[66:67], v[158:159], v[14:15], v[66:67]
	s_nop 0
	v_pk_add_f32 v[68:69], v[64:65], v[66:67]
	s_nop 0
	v_add_f32_e32 v70, v68, v69
	v_sub_f32_e32 v14, v14, v70
	ds_read_b128 v[144:147], v201 offset:39232
	s_waitcnt lgkmcnt(12)
	v_pk_mul_f32 v[64:65], v[96:97], v[0:1]
	v_pk_mul_f32 v[66:67], v[98:99], v[2:3]
	ds_read_b128 v[148:151], v201 offset:39424
	s_waitcnt lgkmcnt(12)
	v_pk_fma_f32 v[64:65], v[100:101], v[4:5], v[64:65]
	v_pk_fma_f32 v[66:67], v[102:103], v[6:7], v[66:67]
	ds_read_b128 v[152:155], v201 offset:39440
	s_waitcnt lgkmcnt(12)
	v_pk_fma_f32 v[64:65], v[104:105], v[8:9], v[64:65]
	v_pk_fma_f32 v[66:67], v[106:107], v[10:11], v[66:67]
	ds_read_b128 v[156:159], v201 offset:39456
	s_waitcnt lgkmcnt(12)
	v_pk_fma_f32 v[64:65], v[108:109], v[12:13], v[64:65]
	v_pk_fma_f32 v[66:67], v[110:111], v[14:15], v[66:67]
	s_nop 0
	v_pk_add_f32 v[68:69], v[64:65], v[66:67]
	s_nop 0
	v_add_f32_e32 v70, v68, v69
	v_sub_f32_e32 v15, v15, v70
	ds_read_b128 v[96:99], v201 offset:39472
	s_waitcnt lgkmcnt(12)
	v_pk_mul_f32 v[64:65], v[112:113], v[0:1]
	v_pk_mul_f32 v[66:67], v[114:115], v[2:3]
	ds_read_b128 v[100:103], v201 offset:39488
	s_waitcnt lgkmcnt(12)
	v_pk_fma_f32 v[64:65], v[116:117], v[4:5], v[64:65]
	v_pk_fma_f32 v[66:67], v[118:119], v[6:7], v[66:67]
	ds_read_b128 v[104:107], v201 offset:39680
	s_waitcnt lgkmcnt(12)
	v_pk_fma_f32 v[64:65], v[120:121], v[8:9], v[64:65]
	v_pk_fma_f32 v[66:67], v[122:123], v[10:11], v[66:67]
	ds_read_b128 v[108:111], v201 offset:39696
	s_waitcnt lgkmcnt(12)
	v_pk_fma_f32 v[64:65], v[124:125], v[12:13], v[64:65]
	v_pk_fma_f32 v[66:67], v[126:127], v[14:15], v[66:67]
	s_nop 0
	v_pk_add_f32 v[68:69], v[64:65], v[66:67]
	s_nop 0
	v_add_f32_e32 v70, v68, v69
	v_sub_f32_e32 v16, v16, v70
	ds_read_b128 v[112:115], v201 offset:39712
	s_waitcnt lgkmcnt(12)
	v_pk_mul_f32 v[64:65], v[128:129], v[0:1]
	v_pk_mul_f32 v[66:67], v[130:131], v[2:3]
	ds_read_b128 v[116:119], v201 offset:39728
	s_waitcnt lgkmcnt(12)
	v_pk_fma_f32 v[64:65], v[132:133], v[4:5], v[64:65]
	v_pk_fma_f32 v[66:67], v[134:135], v[6:7], v[66:67]
	ds_read_b128 v[120:123], v201 offset:39744
	s_waitcnt lgkmcnt(12)
	v_pk_fma_f32 v[64:65], v[136:137], v[8:9], v[64:65]
	v_pk_fma_f32 v[66:67], v[138:139], v[10:11], v[66:67]
	ds_read_b128 v[124:127], v201 offset:39936
	s_waitcnt lgkmcnt(12)
	v_pk_fma_f32 v[64:65], v[140:141], v[12:13], v[64:65]
	v_pk_fma_f32 v[66:67], v[142:143], v[14:15], v[66:67]
	ds_read_b128 v[128:131], v201 offset:39952
	s_waitcnt lgkmcnt(12)
	v_pk_fma_f32 v[64:65], v[144:145], v[16:17], v[64:65]
	v_pk_fma_f32 v[66:67], v[146:147], v[18:19], v[66:67]
	s_nop 0
	v_pk_add_f32 v[68:69], v[64:65], v[66:67]
	s_nop 0
	v_add_f32_e32 v70, v68, v69
	v_sub_f32_e32 v17, v17, v70
	ds_read_b128 v[132:135], v201 offset:39968
	s_waitcnt lgkmcnt(12)
	v_pk_mul_f32 v[64:65], v[148:149], v[0:1]
	v_pk_mul_f32 v[66:67], v[150:151], v[2:3]
	ds_read_b128 v[136:139], v201 offset:39984
	s_waitcnt lgkmcnt(12)
	v_pk_fma_f32 v[64:65], v[152:153], v[4:5], v[64:65]
	v_pk_fma_f32 v[66:67], v[154:155], v[6:7], v[66:67]
	ds_read_b128 v[140:143], v201 offset:40000
	s_waitcnt lgkmcnt(12)
	v_pk_fma_f32 v[64:65], v[156:157], v[8:9], v[64:65]
	v_pk_fma_f32 v[66:67], v[158:159], v[10:11], v[66:67]
	ds_read_b128 v[144:147], v201 offset:40192
	s_waitcnt lgkmcnt(12)
	v_pk_fma_f32 v[64:65], v[96:97], v[12:13], v[64:65]
	v_pk_fma_f32 v[66:67], v[98:99], v[14:15], v[66:67]
	ds_read_b128 v[148:151], v201 offset:40208
	s_waitcnt lgkmcnt(12)
	v_pk_fma_f32 v[64:65], v[100:101], v[16:17], v[64:65]
	v_pk_fma_f32 v[66:67], v[102:103], v[18:19], v[66:67]
	s_nop 0
	v_pk_add_f32 v[68:69], v[64:65], v[66:67]
	s_nop 0
	v_add_f32_e32 v70, v68, v69
	v_sub_f32_e32 v18, v18, v70
	ds_read_b128 v[152:155], v201 offset:40224
	s_waitcnt lgkmcnt(12)
	v_pk_mul_f32 v[64:65], v[104:105], v[0:1]
	v_pk_mul_f32 v[66:67], v[106:107], v[2:3]
	ds_read_b128 v[156:159], v201 offset:40240
	s_waitcnt lgkmcnt(12)
	v_pk_fma_f32 v[64:65], v[108:109], v[4:5], v[64:65]
	v_pk_fma_f32 v[66:67], v[110:111], v[6:7], v[66:67]
	ds_read_b128 v[96:99], v201 offset:40256
	s_waitcnt lgkmcnt(12)
	v_pk_fma_f32 v[64:65], v[112:113], v[8:9], v[64:65]
	v_pk_fma_f32 v[66:67], v[114:115], v[10:11], v[66:67]
	ds_read_b128 v[100:103], v201 offset:40272
	s_waitcnt lgkmcnt(12)
	v_pk_fma_f32 v[64:65], v[116:117], v[12:13], v[64:65]
	v_pk_fma_f32 v[66:67], v[118:119], v[14:15], v[66:67]
	ds_read_b128 v[104:107], v201 offset:40448
	s_waitcnt lgkmcnt(12)
	v_pk_fma_f32 v[64:65], v[120:121], v[16:17], v[64:65]
	v_pk_fma_f32 v[66:67], v[122:123], v[18:19], v[66:67]
	s_nop 0
	v_pk_add_f32 v[68:69], v[64:65], v[66:67]
	s_nop 0
	v_add_f32_e32 v70, v68, v69
	v_sub_f32_e32 v19, v19, v70
	ds_read_b128 v[108:111], v201 offset:40464
	s_waitcnt lgkmcnt(12)
	v_pk_mul_f32 v[64:65], v[124:125], v[0:1]
	v_pk_mul_f32 v[66:67], v[126:127], v[2:3]
	ds_read_b128 v[112:115], v201 offset:40480
	s_waitcnt lgkmcnt(12)
	v_pk_fma_f32 v[64:65], v[128:129], v[4:5], v[64:65]
	v_pk_fma_f32 v[66:67], v[130:131], v[6:7], v[66:67]
	ds_read_b128 v[116:119], v201 offset:40496
	s_waitcnt lgkmcnt(12)
	v_pk_fma_f32 v[64:65], v[132:133], v[8:9], v[64:65]
	v_pk_fma_f32 v[66:67], v[134:135], v[10:11], v[66:67]
	ds_read_b128 v[120:123], v201 offset:40512
	s_waitcnt lgkmcnt(12)
	v_pk_fma_f32 v[64:65], v[136:137], v[12:13], v[64:65]
	v_pk_fma_f32 v[66:67], v[138:139], v[14:15], v[66:67]
	ds_read_b128 v[124:127], v201 offset:40528
	s_waitcnt lgkmcnt(12)
	v_pk_fma_f32 v[64:65], v[140:141], v[16:17], v[64:65]
	v_pk_fma_f32 v[66:67], v[142:143], v[18:19], v[66:67]
	s_nop 0
	v_pk_add_f32 v[68:69], v[64:65], v[66:67]
	s_nop 0
	v_add_f32_e32 v70, v68, v69
	v_sub_f32_e32 v20, v20, v70
	ds_read_b128 v[128:131], v201 offset:40704
	s_waitcnt lgkmcnt(12)
	v_pk_mul_f32 v[64:65], v[144:145], v[0:1]
	v_pk_mul_f32 v[66:67], v[146:147], v[2:3]
	ds_read_b128 v[132:135], v201 offset:40720
	s_waitcnt lgkmcnt(12)
	v_pk_fma_f32 v[64:65], v[148:149], v[4:5], v[64:65]
	v_pk_fma_f32 v[66:67], v[150:151], v[6:7], v[66:67]
	ds_read_b128 v[136:139], v201 offset:40736
	s_waitcnt lgkmcnt(12)
	v_pk_fma_f32 v[64:65], v[152:153], v[8:9], v[64:65]
	v_pk_fma_f32 v[66:67], v[154:155], v[10:11], v[66:67]
	ds_read_b128 v[140:143], v201 offset:40752
	s_waitcnt lgkmcnt(12)
	v_pk_fma_f32 v[64:65], v[156:157], v[12:13], v[64:65]
	v_pk_fma_f32 v[66:67], v[158:159], v[14:15], v[66:67]
	ds_read_b128 v[144:147], v201 offset:40768
	s_waitcnt lgkmcnt(12)
	v_pk_fma_f32 v[64:65], v[96:97], v[16:17], v[64:65]
	v_pk_fma_f32 v[66:67], v[98:99], v[18:19], v[66:67]
	ds_read_b128 v[148:151], v201 offset:40784
	s_waitcnt lgkmcnt(12)
	v_pk_fma_f32 v[64:65], v[100:101], v[20:21], v[64:65]
	v_pk_fma_f32 v[66:67], v[102:103], v[22:23], v[66:67]
	s_nop 0
	v_pk_add_f32 v[68:69], v[64:65], v[66:67]
	s_nop 0
	v_add_f32_e32 v70, v68, v69
	v_sub_f32_e32 v21, v21, v70
	ds_read_b128 v[152:155], v201 offset:40960
	s_waitcnt lgkmcnt(12)
	v_pk_mul_f32 v[64:65], v[104:105], v[0:1]
	v_pk_mul_f32 v[66:67], v[106:107], v[2:3]
	ds_read_b128 v[156:159], v201 offset:40976
	s_waitcnt lgkmcnt(12)
	v_pk_fma_f32 v[64:65], v[108:109], v[4:5], v[64:65]
	v_pk_fma_f32 v[66:67], v[110:111], v[6:7], v[66:67]
	ds_read_b128 v[96:99], v201 offset:40992
	s_waitcnt lgkmcnt(12)
	v_pk_fma_f32 v[64:65], v[112:113], v[8:9], v[64:65]
	v_pk_fma_f32 v[66:67], v[114:115], v[10:11], v[66:67]
	ds_read_b128 v[100:103], v201 offset:41008
	s_waitcnt lgkmcnt(12)
	v_pk_fma_f32 v[64:65], v[116:117], v[12:13], v[64:65]
	v_pk_fma_f32 v[66:67], v[118:119], v[14:15], v[66:67]
	ds_read_b128 v[104:107], v201 offset:41024
	s_waitcnt lgkmcnt(12)
	v_pk_fma_f32 v[64:65], v[120:121], v[16:17], v[64:65]
	v_pk_fma_f32 v[66:67], v[122:123], v[18:19], v[66:67]
	ds_read_b128 v[108:111], v201 offset:41040
	s_waitcnt lgkmcnt(12)
	v_pk_fma_f32 v[64:65], v[124:125], v[20:21], v[64:65]
	v_pk_fma_f32 v[66:67], v[126:127], v[22:23], v[66:67]
	s_nop 0
	v_pk_add_f32 v[68:69], v[64:65], v[66:67]
	s_nop 0
	v_add_f32_e32 v70, v68, v69
	v_sub_f32_e32 v22, v22, v70
	ds_read_b128 v[112:115], v201 offset:41216
	s_waitcnt lgkmcnt(12)
	v_pk_mul_f32 v[64:65], v[128:129], v[0:1]
	v_pk_mul_f32 v[66:67], v[130:131], v[2:3]
	ds_read_b128 v[116:119], v201 offset:41232
	s_waitcnt lgkmcnt(12)
	v_pk_fma_f32 v[64:65], v[132:133], v[4:5], v[64:65]
	v_pk_fma_f32 v[66:67], v[134:135], v[6:7], v[66:67]
	ds_read_b128 v[120:123], v201 offset:41248
	s_waitcnt lgkmcnt(12)
	v_pk_fma_f32 v[64:65], v[136:137], v[8:9], v[64:65]
	v_pk_fma_f32 v[66:67], v[138:139], v[10:11], v[66:67]
	ds_read_b128 v[124:127], v201 offset:41264
	s_waitcnt lgkmcnt(12)
	v_pk_fma_f32 v[64:65], v[140:141], v[12:13], v[64:65]
	v_pk_fma_f32 v[66:67], v[142:143], v[14:15], v[66:67]
	ds_read_b128 v[128:131], v201 offset:41280
	s_waitcnt lgkmcnt(12)
	v_pk_fma_f32 v[64:65], v[144:145], v[16:17], v[64:65]
	v_pk_fma_f32 v[66:67], v[146:147], v[18:19], v[66:67]
	ds_read_b128 v[132:135], v201 offset:41296
	s_waitcnt lgkmcnt(12)
	v_pk_fma_f32 v[64:65], v[148:149], v[20:21], v[64:65]
	v_pk_fma_f32 v[66:67], v[150:151], v[22:23], v[66:67]
	s_nop 0
	v_pk_add_f32 v[68:69], v[64:65], v[66:67]
	s_nop 0
	v_add_f32_e32 v70, v68, v69
	v_sub_f32_e32 v23, v23, v70
	ds_read_b128 v[136:139], v201 offset:41312
	s_waitcnt lgkmcnt(12)
	v_pk_mul_f32 v[64:65], v[152:153], v[0:1]
	v_pk_mul_f32 v[66:67], v[154:155], v[2:3]
	ds_read_b128 v[140:143], v201 offset:41472
	s_waitcnt lgkmcnt(12)
	v_pk_fma_f32 v[64:65], v[156:157], v[4:5], v[64:65]
	v_pk_fma_f32 v[66:67], v[158:159], v[6:7], v[66:67]
	ds_read_b128 v[144:147], v201 offset:41488
	s_waitcnt lgkmcnt(12)
	v_pk_fma_f32 v[64:65], v[96:97], v[8:9], v[64:65]
	v_pk_fma_f32 v[66:67], v[98:99], v[10:11], v[66:67]
	ds_read_b128 v[148:151], v201 offset:41504
	s_waitcnt lgkmcnt(12)
	v_pk_fma_f32 v[64:65], v[100:101], v[12:13], v[64:65]
	v_pk_fma_f32 v[66:67], v[102:103], v[14:15], v[66:67]
	ds_read_b128 v[152:155], v201 offset:41520
	s_waitcnt lgkmcnt(12)
	v_pk_fma_f32 v[64:65], v[104:105], v[16:17], v[64:65]
	v_pk_fma_f32 v[66:67], v[106:107], v[18:19], v[66:67]
	ds_read_b128 v[156:159], v201 offset:41536
	s_waitcnt lgkmcnt(12)
	v_pk_fma_f32 v[64:65], v[108:109], v[20:21], v[64:65]
	v_pk_fma_f32 v[66:67], v[110:111], v[22:23], v[66:67]
	s_nop 0
	v_pk_add_f32 v[68:69], v[64:65], v[66:67]
	s_nop 0
	v_add_f32_e32 v70, v68, v69
	v_sub_f32_e32 v24, v24, v70
	ds_read_b128 v[96:99], v201 offset:41552
	s_waitcnt lgkmcnt(12)
	v_pk_mul_f32 v[64:65], v[112:113], v[0:1]
	v_pk_mul_f32 v[66:67], v[114:115], v[2:3]
	ds_read_b128 v[100:103], v201 offset:41568
	s_waitcnt lgkmcnt(12)
	v_pk_fma_f32 v[64:65], v[116:117], v[4:5], v[64:65]
	v_pk_fma_f32 v[66:67], v[118:119], v[6:7], v[66:67]
	ds_read_b128 v[104:107], v201 offset:41728
	s_waitcnt lgkmcnt(12)
	v_pk_fma_f32 v[64:65], v[120:121], v[8:9], v[64:65]
	v_pk_fma_f32 v[66:67], v[122:123], v[10:11], v[66:67]
	ds_read_b128 v[108:111], v201 offset:41744
	s_waitcnt lgkmcnt(12)
	v_pk_fma_f32 v[64:65], v[124:125], v[12:13], v[64:65]
	v_pk_fma_f32 v[66:67], v[126:127], v[14:15], v[66:67]
	ds_read_b128 v[112:115], v201 offset:41760
	s_waitcnt lgkmcnt(12)
	v_pk_fma_f32 v[64:65], v[128:129], v[16:17], v[64:65]
	v_pk_fma_f32 v[66:67], v[130:131], v[18:19], v[66:67]
	ds_read_b128 v[116:119], v201 offset:41776
	s_waitcnt lgkmcnt(12)
	v_pk_fma_f32 v[64:65], v[132:133], v[20:21], v[64:65]
	v_pk_fma_f32 v[66:67], v[134:135], v[22:23], v[66:67]
	ds_read_b128 v[120:123], v201 offset:41792
	s_waitcnt lgkmcnt(12)
	v_pk_fma_f32 v[64:65], v[136:137], v[24:25], v[64:65]
	v_pk_fma_f32 v[66:67], v[138:139], v[26:27], v[66:67]
	s_nop 0
	v_pk_add_f32 v[68:69], v[64:65], v[66:67]
	s_nop 0
	v_add_f32_e32 v70, v68, v69
	v_sub_f32_e32 v25, v25, v70
	ds_read_b128 v[124:127], v201 offset:41808
	s_waitcnt lgkmcnt(12)
	v_pk_mul_f32 v[64:65], v[140:141], v[0:1]
	v_pk_mul_f32 v[66:67], v[142:143], v[2:3]
	ds_read_b128 v[128:131], v201 offset:41824
	s_waitcnt lgkmcnt(12)
	v_pk_fma_f32 v[64:65], v[144:145], v[4:5], v[64:65]
	v_pk_fma_f32 v[66:67], v[146:147], v[6:7], v[66:67]
	ds_read_b128 v[132:135], v201 offset:41984
	s_waitcnt lgkmcnt(12)
	v_pk_fma_f32 v[64:65], v[148:149], v[8:9], v[64:65]
	v_pk_fma_f32 v[66:67], v[150:151], v[10:11], v[66:67]
	ds_read_b128 v[136:139], v201 offset:42000
	s_waitcnt lgkmcnt(12)
	v_pk_fma_f32 v[64:65], v[152:153], v[12:13], v[64:65]
	v_pk_fma_f32 v[66:67], v[154:155], v[14:15], v[66:67]
	ds_read_b128 v[140:143], v201 offset:42016
	s_waitcnt lgkmcnt(12)
	v_pk_fma_f32 v[64:65], v[156:157], v[16:17], v[64:65]
	v_pk_fma_f32 v[66:67], v[158:159], v[18:19], v[66:67]
	ds_read_b128 v[144:147], v201 offset:42032
	s_waitcnt lgkmcnt(12)
	v_pk_fma_f32 v[64:65], v[96:97], v[20:21], v[64:65]
	v_pk_fma_f32 v[66:67], v[98:99], v[22:23], v[66:67]
	ds_read_b128 v[148:151], v201 offset:42048
	s_waitcnt lgkmcnt(12)
	v_pk_fma_f32 v[64:65], v[100:101], v[24:25], v[64:65]
	v_pk_fma_f32 v[66:67], v[102:103], v[26:27], v[66:67]
	s_nop 0
	v_pk_add_f32 v[68:69], v[64:65], v[66:67]
	s_nop 0
	v_add_f32_e32 v70, v68, v69
	v_sub_f32_e32 v26, v26, v70
	ds_read_b128 v[152:155], v201 offset:42064
	s_waitcnt lgkmcnt(12)
	v_pk_mul_f32 v[64:65], v[104:105], v[0:1]
	v_pk_mul_f32 v[66:67], v[106:107], v[2:3]
	ds_read_b128 v[156:159], v201 offset:42080
	s_waitcnt lgkmcnt(12)
	v_pk_fma_f32 v[64:65], v[108:109], v[4:5], v[64:65]
	v_pk_fma_f32 v[66:67], v[110:111], v[6:7], v[66:67]
	ds_read_b128 v[96:99], v201 offset:42240
	s_waitcnt lgkmcnt(12)
	v_pk_fma_f32 v[64:65], v[112:113], v[8:9], v[64:65]
	v_pk_fma_f32 v[66:67], v[114:115], v[10:11], v[66:67]
	ds_read_b128 v[100:103], v201 offset:42256
	s_waitcnt lgkmcnt(12)
	v_pk_fma_f32 v[64:65], v[116:117], v[12:13], v[64:65]
	v_pk_fma_f32 v[66:67], v[118:119], v[14:15], v[66:67]
	ds_read_b128 v[104:107], v201 offset:42272
	s_waitcnt lgkmcnt(12)
	v_pk_fma_f32 v[64:65], v[120:121], v[16:17], v[64:65]
	v_pk_fma_f32 v[66:67], v[122:123], v[18:19], v[66:67]
	ds_read_b128 v[108:111], v201 offset:42288
	s_waitcnt lgkmcnt(12)
	v_pk_fma_f32 v[64:65], v[124:125], v[20:21], v[64:65]
	v_pk_fma_f32 v[66:67], v[126:127], v[22:23], v[66:67]
	ds_read_b128 v[112:115], v201 offset:42304
	s_waitcnt lgkmcnt(12)
	v_pk_fma_f32 v[64:65], v[128:129], v[24:25], v[64:65]
	v_pk_fma_f32 v[66:67], v[130:131], v[26:27], v[66:67]
	s_nop 0
	v_pk_add_f32 v[68:69], v[64:65], v[66:67]
	s_nop 0
	v_add_f32_e32 v70, v68, v69
	v_sub_f32_e32 v27, v27, v70
	ds_read_b128 v[116:119], v201 offset:42320
	s_waitcnt lgkmcnt(12)
	v_pk_mul_f32 v[64:65], v[132:133], v[0:1]
	v_pk_mul_f32 v[66:67], v[134:135], v[2:3]
	ds_read_b128 v[120:123], v201 offset:42336
	s_waitcnt lgkmcnt(12)
	v_pk_fma_f32 v[64:65], v[136:137], v[4:5], v[64:65]
	v_pk_fma_f32 v[66:67], v[138:139], v[6:7], v[66:67]
	ds_read_b128 v[124:127], v201 offset:42352
	s_waitcnt lgkmcnt(12)
	v_pk_fma_f32 v[64:65], v[140:141], v[8:9], v[64:65]
	v_pk_fma_f32 v[66:67], v[142:143], v[10:11], v[66:67]
	ds_read_b128 v[128:131], v201 offset:42496
	s_waitcnt lgkmcnt(12)
	v_pk_fma_f32 v[64:65], v[144:145], v[12:13], v[64:65]
	v_pk_fma_f32 v[66:67], v[146:147], v[14:15], v[66:67]
	ds_read_b128 v[132:135], v201 offset:42512
	s_waitcnt lgkmcnt(12)
	v_pk_fma_f32 v[64:65], v[148:149], v[16:17], v[64:65]
	v_pk_fma_f32 v[66:67], v[150:151], v[18:19], v[66:67]
	ds_read_b128 v[136:139], v201 offset:42528
	s_waitcnt lgkmcnt(12)
	v_pk_fma_f32 v[64:65], v[152:153], v[20:21], v[64:65]
	v_pk_fma_f32 v[66:67], v[154:155], v[22:23], v[66:67]
	ds_read_b128 v[140:143], v201 offset:42544
	s_waitcnt lgkmcnt(12)
	v_pk_fma_f32 v[64:65], v[156:157], v[24:25], v[64:65]
	v_pk_fma_f32 v[66:67], v[158:159], v[26:27], v[66:67]
	s_nop 0
	v_pk_add_f32 v[68:69], v[64:65], v[66:67]
	s_nop 0
	v_add_f32_e32 v70, v68, v69
	v_sub_f32_e32 v28, v28, v70
	ds_read_b128 v[144:147], v201 offset:42560
	s_waitcnt lgkmcnt(12)
	v_pk_mul_f32 v[64:65], v[96:97], v[0:1]
	v_pk_mul_f32 v[66:67], v[98:99], v[2:3]
	ds_read_b128 v[148:151], v201 offset:42576
	s_waitcnt lgkmcnt(12)
	v_pk_fma_f32 v[64:65], v[100:101], v[4:5], v[64:65]
	v_pk_fma_f32 v[66:67], v[102:103], v[6:7], v[66:67]
	ds_read_b128 v[152:155], v201 offset:42592
	s_waitcnt lgkmcnt(12)
	v_pk_fma_f32 v[64:65], v[104:105], v[8:9], v[64:65]
	v_pk_fma_f32 v[66:67], v[106:107], v[10:11], v[66:67]
	ds_read_b128 v[156:159], v201 offset:42608
	s_waitcnt lgkmcnt(12)
	v_pk_fma_f32 v[64:65], v[108:109], v[12:13], v[64:65]
	v_pk_fma_f32 v[66:67], v[110:111], v[14:15], v[66:67]
	ds_read_b128 v[96:99], v201 offset:42752
	s_waitcnt lgkmcnt(12)
	v_pk_fma_f32 v[64:65], v[112:113], v[16:17], v[64:65]
	v_pk_fma_f32 v[66:67], v[114:115], v[18:19], v[66:67]
	ds_read_b128 v[100:103], v201 offset:42768
	s_waitcnt lgkmcnt(12)
	v_pk_fma_f32 v[64:65], v[116:117], v[20:21], v[64:65]
	v_pk_fma_f32 v[66:67], v[118:119], v[22:23], v[66:67]
	ds_read_b128 v[104:107], v201 offset:42784
	s_waitcnt lgkmcnt(12)
	v_pk_fma_f32 v[64:65], v[120:121], v[24:25], v[64:65]
	v_pk_fma_f32 v[66:67], v[122:123], v[26:27], v[66:67]
	ds_read_b128 v[108:111], v201 offset:42800
	s_waitcnt lgkmcnt(12)
	v_pk_fma_f32 v[64:65], v[124:125], v[28:29], v[64:65]
	v_pk_fma_f32 v[66:67], v[126:127], v[30:31], v[66:67]
	s_nop 0
	v_pk_add_f32 v[68:69], v[64:65], v[66:67]
	s_nop 0
	v_add_f32_e32 v70, v68, v69
	v_sub_f32_e32 v29, v29, v70
	ds_read_b128 v[112:115], v201 offset:42816
	s_waitcnt lgkmcnt(12)
	v_pk_mul_f32 v[64:65], v[128:129], v[0:1]
	v_pk_mul_f32 v[66:67], v[130:131], v[2:3]
	ds_read_b128 v[116:119], v201 offset:42832
	s_waitcnt lgkmcnt(12)
	v_pk_fma_f32 v[64:65], v[132:133], v[4:5], v[64:65]
	v_pk_fma_f32 v[66:67], v[134:135], v[6:7], v[66:67]
	ds_read_b128 v[120:123], v201 offset:42848
	s_waitcnt lgkmcnt(12)
	v_pk_fma_f32 v[64:65], v[136:137], v[8:9], v[64:65]
	v_pk_fma_f32 v[66:67], v[138:139], v[10:11], v[66:67]
	ds_read_b128 v[124:127], v201 offset:42864
	s_waitcnt lgkmcnt(12)
	v_pk_fma_f32 v[64:65], v[140:141], v[12:13], v[64:65]
	v_pk_fma_f32 v[66:67], v[142:143], v[14:15], v[66:67]
	ds_read_b128 v[128:131], v201 offset:43008
	s_waitcnt lgkmcnt(12)
	v_pk_fma_f32 v[64:65], v[144:145], v[16:17], v[64:65]
	v_pk_fma_f32 v[66:67], v[146:147], v[18:19], v[66:67]
	ds_read_b128 v[132:135], v201 offset:43024
	s_waitcnt lgkmcnt(12)
	v_pk_fma_f32 v[64:65], v[148:149], v[20:21], v[64:65]
	v_pk_fma_f32 v[66:67], v[150:151], v[22:23], v[66:67]
	ds_read_b128 v[136:139], v201 offset:43040
	s_waitcnt lgkmcnt(12)
	v_pk_fma_f32 v[64:65], v[152:153], v[24:25], v[64:65]
	v_pk_fma_f32 v[66:67], v[154:155], v[26:27], v[66:67]
	ds_read_b128 v[140:143], v201 offset:43056
	s_waitcnt lgkmcnt(12)
	v_pk_fma_f32 v[64:65], v[156:157], v[28:29], v[64:65]
	v_pk_fma_f32 v[66:67], v[158:159], v[30:31], v[66:67]
	s_nop 0
	v_pk_add_f32 v[68:69], v[64:65], v[66:67]
	s_nop 0
	v_add_f32_e32 v70, v68, v69
	v_sub_f32_e32 v30, v30, v70
	ds_read_b128 v[144:147], v201 offset:43072
	s_waitcnt lgkmcnt(12)
	v_pk_mul_f32 v[64:65], v[96:97], v[0:1]
	v_pk_mul_f32 v[66:67], v[98:99], v[2:3]
	ds_read_b128 v[148:151], v201 offset:43088
	s_waitcnt lgkmcnt(12)
	v_pk_fma_f32 v[64:65], v[100:101], v[4:5], v[64:65]
	v_pk_fma_f32 v[66:67], v[102:103], v[6:7], v[66:67]
	ds_read_b128 v[152:155], v201 offset:43104
	s_waitcnt lgkmcnt(12)
	v_pk_fma_f32 v[64:65], v[104:105], v[8:9], v[64:65]
	v_pk_fma_f32 v[66:67], v[106:107], v[10:11], v[66:67]
	ds_read_b128 v[156:159], v201 offset:43120
	s_waitcnt lgkmcnt(12)
	v_pk_fma_f32 v[64:65], v[108:109], v[12:13], v[64:65]
	v_pk_fma_f32 v[66:67], v[110:111], v[14:15], v[66:67]
	ds_read_b128 v[96:99], v201 offset:43264
	s_waitcnt lgkmcnt(12)
	v_pk_fma_f32 v[64:65], v[112:113], v[16:17], v[64:65]
	v_pk_fma_f32 v[66:67], v[114:115], v[18:19], v[66:67]
	ds_read_b128 v[100:103], v201 offset:43280
	s_waitcnt lgkmcnt(12)
	v_pk_fma_f32 v[64:65], v[116:117], v[20:21], v[64:65]
	v_pk_fma_f32 v[66:67], v[118:119], v[22:23], v[66:67]
	ds_read_b128 v[104:107], v201 offset:43296
	s_waitcnt lgkmcnt(12)
	v_pk_fma_f32 v[64:65], v[120:121], v[24:25], v[64:65]
	v_pk_fma_f32 v[66:67], v[122:123], v[26:27], v[66:67]
	ds_read_b128 v[108:111], v201 offset:43312
	s_waitcnt lgkmcnt(12)
	v_pk_fma_f32 v[64:65], v[124:125], v[28:29], v[64:65]
	v_pk_fma_f32 v[66:67], v[126:127], v[30:31], v[66:67]
	s_nop 0
	v_pk_add_f32 v[68:69], v[64:65], v[66:67]
	s_nop 0
	v_add_f32_e32 v70, v68, v69
	v_sub_f32_e32 v31, v31, v70
	ds_read_b128 v[112:115], v201 offset:43328
	s_waitcnt lgkmcnt(12)
	v_pk_mul_f32 v[64:65], v[128:129], v[0:1]
	v_pk_mul_f32 v[66:67], v[130:131], v[2:3]
	ds_read_b128 v[116:119], v201 offset:43344
	s_waitcnt lgkmcnt(12)
	v_pk_fma_f32 v[64:65], v[132:133], v[4:5], v[64:65]
	v_pk_fma_f32 v[66:67], v[134:135], v[6:7], v[66:67]
	ds_read_b128 v[120:123], v201 offset:43360
	s_waitcnt lgkmcnt(12)
	v_pk_fma_f32 v[64:65], v[136:137], v[8:9], v[64:65]
	v_pk_fma_f32 v[66:67], v[138:139], v[10:11], v[66:67]
	ds_read_b128 v[124:127], v201 offset:43376
	s_waitcnt lgkmcnt(12)
	v_pk_fma_f32 v[64:65], v[140:141], v[12:13], v[64:65]
	v_pk_fma_f32 v[66:67], v[142:143], v[14:15], v[66:67]
	ds_read_b128 v[128:131], v201 offset:43392
	s_waitcnt lgkmcnt(12)
	v_pk_fma_f32 v[64:65], v[144:145], v[16:17], v[64:65]
	v_pk_fma_f32 v[66:67], v[146:147], v[18:19], v[66:67]
	ds_read_b128 v[132:135], v201 offset:43520
	s_waitcnt lgkmcnt(12)
	v_pk_fma_f32 v[64:65], v[148:149], v[20:21], v[64:65]
	v_pk_fma_f32 v[66:67], v[150:151], v[22:23], v[66:67]
	ds_read_b128 v[136:139], v201 offset:43536
	s_waitcnt lgkmcnt(12)
	v_pk_fma_f32 v[64:65], v[152:153], v[24:25], v[64:65]
	v_pk_fma_f32 v[66:67], v[154:155], v[26:27], v[66:67]
	ds_read_b128 v[140:143], v201 offset:43552
	s_waitcnt lgkmcnt(12)
	v_pk_fma_f32 v[64:65], v[156:157], v[28:29], v[64:65]
	v_pk_fma_f32 v[66:67], v[158:159], v[30:31], v[66:67]
	s_nop 0
	v_pk_add_f32 v[68:69], v[64:65], v[66:67]
	s_nop 0
	v_add_f32_e32 v70, v68, v69
	v_sub_f32_e32 v32, v32, v70
	ds_read_b128 v[144:147], v201 offset:43568
	s_waitcnt lgkmcnt(12)
	v_pk_mul_f32 v[64:65], v[96:97], v[0:1]
	v_pk_mul_f32 v[66:67], v[98:99], v[2:3]
	ds_read_b128 v[148:151], v201 offset:43584
	s_waitcnt lgkmcnt(12)
	v_pk_fma_f32 v[64:65], v[100:101], v[4:5], v[64:65]
	v_pk_fma_f32 v[66:67], v[102:103], v[6:7], v[66:67]
	ds_read_b128 v[152:155], v201 offset:43600
	s_waitcnt lgkmcnt(12)
	v_pk_fma_f32 v[64:65], v[104:105], v[8:9], v[64:65]
	v_pk_fma_f32 v[66:67], v[106:107], v[10:11], v[66:67]
	ds_read_b128 v[156:159], v201 offset:43616
	s_waitcnt lgkmcnt(12)
	v_pk_fma_f32 v[64:65], v[108:109], v[12:13], v[64:65]
	v_pk_fma_f32 v[66:67], v[110:111], v[14:15], v[66:67]
	ds_read_b128 v[96:99], v201 offset:43632
	s_waitcnt lgkmcnt(12)
	v_pk_fma_f32 v[64:65], v[112:113], v[16:17], v[64:65]
	v_pk_fma_f32 v[66:67], v[114:115], v[18:19], v[66:67]
	ds_read_b128 v[100:103], v201 offset:43648
	s_waitcnt lgkmcnt(12)
	v_pk_fma_f32 v[64:65], v[116:117], v[20:21], v[64:65]
	v_pk_fma_f32 v[66:67], v[118:119], v[22:23], v[66:67]
	ds_read_b128 v[104:107], v201 offset:43776
	s_waitcnt lgkmcnt(12)
	v_pk_fma_f32 v[64:65], v[120:121], v[24:25], v[64:65]
	v_pk_fma_f32 v[66:67], v[122:123], v[26:27], v[66:67]
	ds_read_b128 v[108:111], v201 offset:43792
	s_waitcnt lgkmcnt(12)
	v_pk_fma_f32 v[64:65], v[124:125], v[28:29], v[64:65]
	v_pk_fma_f32 v[66:67], v[126:127], v[30:31], v[66:67]
	ds_read_b128 v[112:115], v201 offset:43808
	s_waitcnt lgkmcnt(12)
	v_pk_fma_f32 v[64:65], v[128:129], v[32:33], v[64:65]
	v_pk_fma_f32 v[66:67], v[130:131], v[34:35], v[66:67]
	s_nop 0
	v_pk_add_f32 v[68:69], v[64:65], v[66:67]
	s_nop 0
	v_add_f32_e32 v70, v68, v69
	v_sub_f32_e32 v33, v33, v70
	ds_read_b128 v[116:119], v201 offset:43824
	s_waitcnt lgkmcnt(12)
	v_pk_mul_f32 v[64:65], v[132:133], v[0:1]
	v_pk_mul_f32 v[66:67], v[134:135], v[2:3]
	ds_read_b128 v[120:123], v201 offset:43840
	s_waitcnt lgkmcnt(12)
	v_pk_fma_f32 v[64:65], v[136:137], v[4:5], v[64:65]
	v_pk_fma_f32 v[66:67], v[138:139], v[6:7], v[66:67]
	ds_read_b128 v[124:127], v201 offset:43856
	s_waitcnt lgkmcnt(12)
	v_pk_fma_f32 v[64:65], v[140:141], v[8:9], v[64:65]
	v_pk_fma_f32 v[66:67], v[142:143], v[10:11], v[66:67]
	ds_read_b128 v[128:131], v201 offset:43872
	s_waitcnt lgkmcnt(12)
	v_pk_fma_f32 v[64:65], v[144:145], v[12:13], v[64:65]
	v_pk_fma_f32 v[66:67], v[146:147], v[14:15], v[66:67]
	ds_read_b128 v[132:135], v201 offset:43888
	s_waitcnt lgkmcnt(12)
	v_pk_fma_f32 v[64:65], v[148:149], v[16:17], v[64:65]
	v_pk_fma_f32 v[66:67], v[150:151], v[18:19], v[66:67]
	ds_read_b128 v[136:139], v201 offset:43904
	s_waitcnt lgkmcnt(12)
	v_pk_fma_f32 v[64:65], v[152:153], v[20:21], v[64:65]
	v_pk_fma_f32 v[66:67], v[154:155], v[22:23], v[66:67]
	ds_read_b128 v[140:143], v201 offset:44032
	s_waitcnt lgkmcnt(12)
	v_pk_fma_f32 v[64:65], v[156:157], v[24:25], v[64:65]
	v_pk_fma_f32 v[66:67], v[158:159], v[26:27], v[66:67]
	ds_read_b128 v[144:147], v201 offset:44048
	s_waitcnt lgkmcnt(12)
	v_pk_fma_f32 v[64:65], v[96:97], v[28:29], v[64:65]
	v_pk_fma_f32 v[66:67], v[98:99], v[30:31], v[66:67]
	ds_read_b128 v[148:151], v201 offset:44064
	s_waitcnt lgkmcnt(12)
	v_pk_fma_f32 v[64:65], v[100:101], v[32:33], v[64:65]
	v_pk_fma_f32 v[66:67], v[102:103], v[34:35], v[66:67]
	s_nop 0
	v_pk_add_f32 v[68:69], v[64:65], v[66:67]
	s_nop 0
	v_add_f32_e32 v70, v68, v69
	v_sub_f32_e32 v34, v34, v70
	ds_read_b128 v[152:155], v201 offset:44080
	s_waitcnt lgkmcnt(12)
	v_pk_mul_f32 v[64:65], v[104:105], v[0:1]
	v_pk_mul_f32 v[66:67], v[106:107], v[2:3]
	ds_read_b128 v[156:159], v201 offset:44096
	s_waitcnt lgkmcnt(12)
	v_pk_fma_f32 v[64:65], v[108:109], v[4:5], v[64:65]
	v_pk_fma_f32 v[66:67], v[110:111], v[6:7], v[66:67]
	ds_read_b128 v[96:99], v201 offset:44112
	s_waitcnt lgkmcnt(12)
	v_pk_fma_f32 v[64:65], v[112:113], v[8:9], v[64:65]
	v_pk_fma_f32 v[66:67], v[114:115], v[10:11], v[66:67]
	ds_read_b128 v[100:103], v201 offset:44128
	s_waitcnt lgkmcnt(12)
	v_pk_fma_f32 v[64:65], v[116:117], v[12:13], v[64:65]
	v_pk_fma_f32 v[66:67], v[118:119], v[14:15], v[66:67]
	ds_read_b128 v[104:107], v201 offset:44144
	s_waitcnt lgkmcnt(12)
	v_pk_fma_f32 v[64:65], v[120:121], v[16:17], v[64:65]
	v_pk_fma_f32 v[66:67], v[122:123], v[18:19], v[66:67]
	ds_read_b128 v[108:111], v201 offset:44160
	s_waitcnt lgkmcnt(12)
	v_pk_fma_f32 v[64:65], v[124:125], v[20:21], v[64:65]
	v_pk_fma_f32 v[66:67], v[126:127], v[22:23], v[66:67]
	ds_read_b128 v[112:115], v201 offset:44288
	s_waitcnt lgkmcnt(12)
	v_pk_fma_f32 v[64:65], v[128:129], v[24:25], v[64:65]
	v_pk_fma_f32 v[66:67], v[130:131], v[26:27], v[66:67]
	ds_read_b128 v[116:119], v201 offset:44304
	s_waitcnt lgkmcnt(12)
	v_pk_fma_f32 v[64:65], v[132:133], v[28:29], v[64:65]
	v_pk_fma_f32 v[66:67], v[134:135], v[30:31], v[66:67]
	ds_read_b128 v[120:123], v201 offset:44320
	s_waitcnt lgkmcnt(12)
	v_pk_fma_f32 v[64:65], v[136:137], v[32:33], v[64:65]
	v_pk_fma_f32 v[66:67], v[138:139], v[34:35], v[66:67]
	s_nop 0
	v_pk_add_f32 v[68:69], v[64:65], v[66:67]
	s_nop 0
	v_add_f32_e32 v70, v68, v69
	v_sub_f32_e32 v35, v35, v70
	ds_read_b128 v[124:127], v201 offset:44336
	s_waitcnt lgkmcnt(12)
	v_pk_mul_f32 v[64:65], v[140:141], v[0:1]
	v_pk_mul_f32 v[66:67], v[142:143], v[2:3]
	ds_read_b128 v[128:131], v201 offset:44352
	s_waitcnt lgkmcnt(12)
	v_pk_fma_f32 v[64:65], v[144:145], v[4:5], v[64:65]
	v_pk_fma_f32 v[66:67], v[146:147], v[6:7], v[66:67]
	ds_read_b128 v[132:135], v201 offset:44368
	s_waitcnt lgkmcnt(12)
	v_pk_fma_f32 v[64:65], v[148:149], v[8:9], v[64:65]
	v_pk_fma_f32 v[66:67], v[150:151], v[10:11], v[66:67]
	ds_read_b128 v[136:139], v201 offset:44384
	s_waitcnt lgkmcnt(12)
	v_pk_fma_f32 v[64:65], v[152:153], v[12:13], v[64:65]
	v_pk_fma_f32 v[66:67], v[154:155], v[14:15], v[66:67]
	ds_read_b128 v[140:143], v201 offset:44400
	s_waitcnt lgkmcnt(12)
	v_pk_fma_f32 v[64:65], v[156:157], v[16:17], v[64:65]
	v_pk_fma_f32 v[66:67], v[158:159], v[18:19], v[66:67]
	ds_read_b128 v[144:147], v201 offset:44416
	s_waitcnt lgkmcnt(12)
	v_pk_fma_f32 v[64:65], v[96:97], v[20:21], v[64:65]
	v_pk_fma_f32 v[66:67], v[98:99], v[22:23], v[66:67]
	ds_read_b128 v[148:151], v201 offset:44432
	s_waitcnt lgkmcnt(12)
	v_pk_fma_f32 v[64:65], v[100:101], v[24:25], v[64:65]
	v_pk_fma_f32 v[66:67], v[102:103], v[26:27], v[66:67]
	ds_read_b128 v[152:155], v201 offset:44544
	s_waitcnt lgkmcnt(12)
	v_pk_fma_f32 v[64:65], v[104:105], v[28:29], v[64:65]
	v_pk_fma_f32 v[66:67], v[106:107], v[30:31], v[66:67]
	ds_read_b128 v[156:159], v201 offset:44560
	s_waitcnt lgkmcnt(12)
	v_pk_fma_f32 v[64:65], v[108:109], v[32:33], v[64:65]
	v_pk_fma_f32 v[66:67], v[110:111], v[34:35], v[66:67]
	s_nop 0
	v_pk_add_f32 v[68:69], v[64:65], v[66:67]
	s_nop 0
	v_add_f32_e32 v70, v68, v69
	v_sub_f32_e32 v36, v36, v70
	ds_read_b128 v[96:99], v201 offset:44576
	s_waitcnt lgkmcnt(12)
	v_pk_mul_f32 v[64:65], v[112:113], v[0:1]
	v_pk_mul_f32 v[66:67], v[114:115], v[2:3]
	ds_read_b128 v[100:103], v201 offset:44592
	s_waitcnt lgkmcnt(12)
	v_pk_fma_f32 v[64:65], v[116:117], v[4:5], v[64:65]
	v_pk_fma_f32 v[66:67], v[118:119], v[6:7], v[66:67]
	ds_read_b128 v[104:107], v201 offset:44608
	s_waitcnt lgkmcnt(12)
	v_pk_fma_f32 v[64:65], v[120:121], v[8:9], v[64:65]
	v_pk_fma_f32 v[66:67], v[122:123], v[10:11], v[66:67]
	ds_read_b128 v[108:111], v201 offset:44624
	s_waitcnt lgkmcnt(12)
	v_pk_fma_f32 v[64:65], v[124:125], v[12:13], v[64:65]
	v_pk_fma_f32 v[66:67], v[126:127], v[14:15], v[66:67]
	ds_read_b128 v[112:115], v201 offset:44640
	s_waitcnt lgkmcnt(12)
	v_pk_fma_f32 v[64:65], v[128:129], v[16:17], v[64:65]
	v_pk_fma_f32 v[66:67], v[130:131], v[18:19], v[66:67]
	ds_read_b128 v[116:119], v201 offset:44656
	s_waitcnt lgkmcnt(12)
	v_pk_fma_f32 v[64:65], v[132:133], v[20:21], v[64:65]
	v_pk_fma_f32 v[66:67], v[134:135], v[22:23], v[66:67]
	ds_read_b128 v[120:123], v201 offset:44672
	s_waitcnt lgkmcnt(12)
	v_pk_fma_f32 v[64:65], v[136:137], v[24:25], v[64:65]
	v_pk_fma_f32 v[66:67], v[138:139], v[26:27], v[66:67]
	ds_read_b128 v[124:127], v201 offset:44688
	s_waitcnt lgkmcnt(12)
	v_pk_fma_f32 v[64:65], v[140:141], v[28:29], v[64:65]
	v_pk_fma_f32 v[66:67], v[142:143], v[30:31], v[66:67]
	ds_read_b128 v[128:131], v201 offset:44800
	s_waitcnt lgkmcnt(12)
	v_pk_fma_f32 v[64:65], v[144:145], v[32:33], v[64:65]
	v_pk_fma_f32 v[66:67], v[146:147], v[34:35], v[66:67]
	ds_read_b128 v[132:135], v201 offset:44816
	s_waitcnt lgkmcnt(12)
	v_pk_fma_f32 v[64:65], v[148:149], v[36:37], v[64:65]
	v_pk_fma_f32 v[66:67], v[150:151], v[38:39], v[66:67]
	s_nop 0
	v_pk_add_f32 v[68:69], v[64:65], v[66:67]
	s_nop 0
	v_add_f32_e32 v70, v68, v69
	v_sub_f32_e32 v37, v37, v70
	ds_read_b128 v[136:139], v201 offset:44832
	s_waitcnt lgkmcnt(12)
	v_pk_mul_f32 v[64:65], v[152:153], v[0:1]
	v_pk_mul_f32 v[66:67], v[154:155], v[2:3]
	ds_read_b128 v[140:143], v201 offset:44848
	s_waitcnt lgkmcnt(12)
	v_pk_fma_f32 v[64:65], v[156:157], v[4:5], v[64:65]
	v_pk_fma_f32 v[66:67], v[158:159], v[6:7], v[66:67]
	ds_read_b128 v[144:147], v201 offset:44864
	s_waitcnt lgkmcnt(12)
	v_pk_fma_f32 v[64:65], v[96:97], v[8:9], v[64:65]
	v_pk_fma_f32 v[66:67], v[98:99], v[10:11], v[66:67]
	ds_read_b128 v[148:151], v201 offset:44880
	s_waitcnt lgkmcnt(12)
	v_pk_fma_f32 v[64:65], v[100:101], v[12:13], v[64:65]
	v_pk_fma_f32 v[66:67], v[102:103], v[14:15], v[66:67]
	ds_read_b128 v[152:155], v201 offset:44896
	s_waitcnt lgkmcnt(12)
	v_pk_fma_f32 v[64:65], v[104:105], v[16:17], v[64:65]
	v_pk_fma_f32 v[66:67], v[106:107], v[18:19], v[66:67]
	ds_read_b128 v[156:159], v201 offset:44912
	s_waitcnt lgkmcnt(12)
	v_pk_fma_f32 v[64:65], v[108:109], v[20:21], v[64:65]
	v_pk_fma_f32 v[66:67], v[110:111], v[22:23], v[66:67]
	ds_read_b128 v[96:99], v201 offset:44928
	s_waitcnt lgkmcnt(12)
	v_pk_fma_f32 v[64:65], v[112:113], v[24:25], v[64:65]
	v_pk_fma_f32 v[66:67], v[114:115], v[26:27], v[66:67]
	ds_read_b128 v[100:103], v201 offset:44944
	s_waitcnt lgkmcnt(12)
	v_pk_fma_f32 v[64:65], v[116:117], v[28:29], v[64:65]
	v_pk_fma_f32 v[66:67], v[118:119], v[30:31], v[66:67]
	ds_read_b128 v[104:107], v201 offset:45056
	s_waitcnt lgkmcnt(12)
	v_pk_fma_f32 v[64:65], v[120:121], v[32:33], v[64:65]
	v_pk_fma_f32 v[66:67], v[122:123], v[34:35], v[66:67]
	ds_read_b128 v[108:111], v201 offset:45072
	s_waitcnt lgkmcnt(12)
	v_pk_fma_f32 v[64:65], v[124:125], v[36:37], v[64:65]
	v_pk_fma_f32 v[66:67], v[126:127], v[38:39], v[66:67]
	s_nop 0
	v_pk_add_f32 v[68:69], v[64:65], v[66:67]
	s_nop 0
	v_add_f32_e32 v70, v68, v69
	v_sub_f32_e32 v38, v38, v70
	ds_read_b128 v[112:115], v201 offset:45088
	s_waitcnt lgkmcnt(12)
	v_pk_mul_f32 v[64:65], v[128:129], v[0:1]
	v_pk_mul_f32 v[66:67], v[130:131], v[2:3]
	ds_read_b128 v[116:119], v201 offset:45104
	s_waitcnt lgkmcnt(12)
	v_pk_fma_f32 v[64:65], v[132:133], v[4:5], v[64:65]
	v_pk_fma_f32 v[66:67], v[134:135], v[6:7], v[66:67]
	ds_read_b128 v[120:123], v201 offset:45120
	s_waitcnt lgkmcnt(12)
	v_pk_fma_f32 v[64:65], v[136:137], v[8:9], v[64:65]
	v_pk_fma_f32 v[66:67], v[138:139], v[10:11], v[66:67]
	ds_read_b128 v[124:127], v201 offset:45136
	s_waitcnt lgkmcnt(12)
	v_pk_fma_f32 v[64:65], v[140:141], v[12:13], v[64:65]
	v_pk_fma_f32 v[66:67], v[142:143], v[14:15], v[66:67]
	ds_read_b128 v[128:131], v201 offset:45152
	s_waitcnt lgkmcnt(12)
	v_pk_fma_f32 v[64:65], v[144:145], v[16:17], v[64:65]
	v_pk_fma_f32 v[66:67], v[146:147], v[18:19], v[66:67]
	ds_read_b128 v[132:135], v201 offset:45168
	s_waitcnt lgkmcnt(12)
	v_pk_fma_f32 v[64:65], v[148:149], v[20:21], v[64:65]
	v_pk_fma_f32 v[66:67], v[150:151], v[22:23], v[66:67]
	ds_read_b128 v[136:139], v201 offset:45184
	s_waitcnt lgkmcnt(12)
	v_pk_fma_f32 v[64:65], v[152:153], v[24:25], v[64:65]
	v_pk_fma_f32 v[66:67], v[154:155], v[26:27], v[66:67]
	ds_read_b128 v[140:143], v201 offset:45200
	s_waitcnt lgkmcnt(12)
	v_pk_fma_f32 v[64:65], v[156:157], v[28:29], v[64:65]
	v_pk_fma_f32 v[66:67], v[158:159], v[30:31], v[66:67]
	ds_read_b128 v[144:147], v201 offset:45312
	s_waitcnt lgkmcnt(12)
	v_pk_fma_f32 v[64:65], v[96:97], v[32:33], v[64:65]
	v_pk_fma_f32 v[66:67], v[98:99], v[34:35], v[66:67]
	ds_read_b128 v[148:151], v201 offset:45328
	s_waitcnt lgkmcnt(12)
	v_pk_fma_f32 v[64:65], v[100:101], v[36:37], v[64:65]
	v_pk_fma_f32 v[66:67], v[102:103], v[38:39], v[66:67]
	s_nop 0
	v_pk_add_f32 v[68:69], v[64:65], v[66:67]
	s_nop 0
	v_add_f32_e32 v70, v68, v69
	v_sub_f32_e32 v39, v39, v70
	ds_read_b128 v[152:155], v201 offset:45344
	s_waitcnt lgkmcnt(12)
	v_pk_mul_f32 v[64:65], v[104:105], v[0:1]
	v_pk_mul_f32 v[66:67], v[106:107], v[2:3]
	ds_read_b128 v[156:159], v201 offset:45360
	s_waitcnt lgkmcnt(12)
	v_pk_fma_f32 v[64:65], v[108:109], v[4:5], v[64:65]
	v_pk_fma_f32 v[66:67], v[110:111], v[6:7], v[66:67]
	ds_read_b128 v[96:99], v201 offset:45376
	s_waitcnt lgkmcnt(12)
	v_pk_fma_f32 v[64:65], v[112:113], v[8:9], v[64:65]
	v_pk_fma_f32 v[66:67], v[114:115], v[10:11], v[66:67]
	ds_read_b128 v[100:103], v201 offset:45392
	s_waitcnt lgkmcnt(12)
	v_pk_fma_f32 v[64:65], v[116:117], v[12:13], v[64:65]
	v_pk_fma_f32 v[66:67], v[118:119], v[14:15], v[66:67]
	ds_read_b128 v[104:107], v201 offset:45408
	s_waitcnt lgkmcnt(12)
	v_pk_fma_f32 v[64:65], v[120:121], v[16:17], v[64:65]
	v_pk_fma_f32 v[66:67], v[122:123], v[18:19], v[66:67]
	ds_read_b128 v[108:111], v201 offset:45424
	s_waitcnt lgkmcnt(12)
	v_pk_fma_f32 v[64:65], v[124:125], v[20:21], v[64:65]
	v_pk_fma_f32 v[66:67], v[126:127], v[22:23], v[66:67]
	ds_read_b128 v[112:115], v201 offset:45440
	s_waitcnt lgkmcnt(12)
	v_pk_fma_f32 v[64:65], v[128:129], v[24:25], v[64:65]
	v_pk_fma_f32 v[66:67], v[130:131], v[26:27], v[66:67]
	ds_read_b128 v[116:119], v201 offset:45456
	s_waitcnt lgkmcnt(12)
	v_pk_fma_f32 v[64:65], v[132:133], v[28:29], v[64:65]
	v_pk_fma_f32 v[66:67], v[134:135], v[30:31], v[66:67]
	ds_read_b128 v[120:123], v201 offset:45472
	s_waitcnt lgkmcnt(12)
	v_pk_fma_f32 v[64:65], v[136:137], v[32:33], v[64:65]
	v_pk_fma_f32 v[66:67], v[138:139], v[34:35], v[66:67]
	ds_read_b128 v[124:127], v201 offset:45568
	s_waitcnt lgkmcnt(12)
	v_pk_fma_f32 v[64:65], v[140:141], v[36:37], v[64:65]
	v_pk_fma_f32 v[66:67], v[142:143], v[38:39], v[66:67]
	s_nop 0
	v_pk_add_f32 v[68:69], v[64:65], v[66:67]
	s_nop 0
	v_add_f32_e32 v70, v68, v69
	v_sub_f32_e32 v40, v40, v70
	ds_read_b128 v[128:131], v201 offset:45584
	s_waitcnt lgkmcnt(12)
	v_pk_mul_f32 v[64:65], v[144:145], v[0:1]
	v_pk_mul_f32 v[66:67], v[146:147], v[2:3]
	ds_read_b128 v[132:135], v201 offset:45600
	s_waitcnt lgkmcnt(12)
	v_pk_fma_f32 v[64:65], v[148:149], v[4:5], v[64:65]
	v_pk_fma_f32 v[66:67], v[150:151], v[6:7], v[66:67]
	ds_read_b128 v[136:139], v201 offset:45616
	s_waitcnt lgkmcnt(12)
	v_pk_fma_f32 v[64:65], v[152:153], v[8:9], v[64:65]
	v_pk_fma_f32 v[66:67], v[154:155], v[10:11], v[66:67]
	ds_read_b128 v[140:143], v201 offset:45632
	s_waitcnt lgkmcnt(12)
	v_pk_fma_f32 v[64:65], v[156:157], v[12:13], v[64:65]
	v_pk_fma_f32 v[66:67], v[158:159], v[14:15], v[66:67]
	ds_read_b128 v[144:147], v201 offset:45648
	s_waitcnt lgkmcnt(12)
	v_pk_fma_f32 v[64:65], v[96:97], v[16:17], v[64:65]
	v_pk_fma_f32 v[66:67], v[98:99], v[18:19], v[66:67]
	ds_read_b128 v[148:151], v201 offset:45664
	s_waitcnt lgkmcnt(12)
	v_pk_fma_f32 v[64:65], v[100:101], v[20:21], v[64:65]
	v_pk_fma_f32 v[66:67], v[102:103], v[22:23], v[66:67]
	ds_read_b128 v[152:155], v201 offset:45680
	s_waitcnt lgkmcnt(12)
	v_pk_fma_f32 v[64:65], v[104:105], v[24:25], v[64:65]
	v_pk_fma_f32 v[66:67], v[106:107], v[26:27], v[66:67]
	ds_read_b128 v[156:159], v201 offset:45696
	s_waitcnt lgkmcnt(12)
	v_pk_fma_f32 v[64:65], v[108:109], v[28:29], v[64:65]
	v_pk_fma_f32 v[66:67], v[110:111], v[30:31], v[66:67]
	ds_read_b128 v[96:99], v201 offset:45712
	s_waitcnt lgkmcnt(12)
	v_pk_fma_f32 v[64:65], v[112:113], v[32:33], v[64:65]
	v_pk_fma_f32 v[66:67], v[114:115], v[34:35], v[66:67]
	ds_read_b128 v[100:103], v201 offset:45728
	s_waitcnt lgkmcnt(12)
	v_pk_fma_f32 v[64:65], v[116:117], v[36:37], v[64:65]
	v_pk_fma_f32 v[66:67], v[118:119], v[38:39], v[66:67]
	ds_read_b128 v[104:107], v201 offset:45824
	s_waitcnt lgkmcnt(12)
	v_pk_fma_f32 v[64:65], v[120:121], v[40:41], v[64:65]
	v_pk_fma_f32 v[66:67], v[122:123], v[42:43], v[66:67]
	s_nop 0
	v_pk_add_f32 v[68:69], v[64:65], v[66:67]
	s_nop 0
	v_add_f32_e32 v70, v68, v69
	v_sub_f32_e32 v41, v41, v70
	ds_read_b128 v[108:111], v201 offset:45840
	s_waitcnt lgkmcnt(12)
	v_pk_mul_f32 v[64:65], v[124:125], v[0:1]
	v_pk_mul_f32 v[66:67], v[126:127], v[2:3]
	ds_read_b128 v[112:115], v201 offset:45856
	s_waitcnt lgkmcnt(12)
	v_pk_fma_f32 v[64:65], v[128:129], v[4:5], v[64:65]
	v_pk_fma_f32 v[66:67], v[130:131], v[6:7], v[66:67]
	ds_read_b128 v[116:119], v201 offset:45872
	s_waitcnt lgkmcnt(12)
	v_pk_fma_f32 v[64:65], v[132:133], v[8:9], v[64:65]
	v_pk_fma_f32 v[66:67], v[134:135], v[10:11], v[66:67]
	ds_read_b128 v[120:123], v201 offset:45888
	s_waitcnt lgkmcnt(12)
	v_pk_fma_f32 v[64:65], v[136:137], v[12:13], v[64:65]
	v_pk_fma_f32 v[66:67], v[138:139], v[14:15], v[66:67]
	ds_read_b128 v[124:127], v201 offset:45904
	s_waitcnt lgkmcnt(12)
	v_pk_fma_f32 v[64:65], v[140:141], v[16:17], v[64:65]
	v_pk_fma_f32 v[66:67], v[142:143], v[18:19], v[66:67]
	ds_read_b128 v[128:131], v201 offset:45920
	s_waitcnt lgkmcnt(12)
	v_pk_fma_f32 v[64:65], v[144:145], v[20:21], v[64:65]
	v_pk_fma_f32 v[66:67], v[146:147], v[22:23], v[66:67]
	ds_read_b128 v[132:135], v201 offset:45936
	s_waitcnt lgkmcnt(12)
	v_pk_fma_f32 v[64:65], v[148:149], v[24:25], v[64:65]
	v_pk_fma_f32 v[66:67], v[150:151], v[26:27], v[66:67]
	ds_read_b128 v[136:139], v201 offset:45952
	s_waitcnt lgkmcnt(12)
	v_pk_fma_f32 v[64:65], v[152:153], v[28:29], v[64:65]
	v_pk_fma_f32 v[66:67], v[154:155], v[30:31], v[66:67]
	ds_read_b128 v[140:143], v201 offset:45968
	s_waitcnt lgkmcnt(12)
	v_pk_fma_f32 v[64:65], v[156:157], v[32:33], v[64:65]
	v_pk_fma_f32 v[66:67], v[158:159], v[34:35], v[66:67]
	ds_read_b128 v[144:147], v201 offset:45984
	s_waitcnt lgkmcnt(12)
	v_pk_fma_f32 v[64:65], v[96:97], v[36:37], v[64:65]
	v_pk_fma_f32 v[66:67], v[98:99], v[38:39], v[66:67]
	ds_read_b128 v[148:151], v201 offset:46080
	s_waitcnt lgkmcnt(12)
	v_pk_fma_f32 v[64:65], v[100:101], v[40:41], v[64:65]
	v_pk_fma_f32 v[66:67], v[102:103], v[42:43], v[66:67]
	s_nop 0
	v_pk_add_f32 v[68:69], v[64:65], v[66:67]
	s_nop 0
	v_add_f32_e32 v70, v68, v69
	v_sub_f32_e32 v42, v42, v70
	ds_read_b128 v[152:155], v201 offset:46096
	s_waitcnt lgkmcnt(12)
	v_pk_mul_f32 v[64:65], v[104:105], v[0:1]
	v_pk_mul_f32 v[66:67], v[106:107], v[2:3]
	ds_read_b128 v[156:159], v201 offset:46112
	s_waitcnt lgkmcnt(12)
	v_pk_fma_f32 v[64:65], v[108:109], v[4:5], v[64:65]
	v_pk_fma_f32 v[66:67], v[110:111], v[6:7], v[66:67]
	ds_read_b128 v[96:99], v201 offset:46128
	s_waitcnt lgkmcnt(12)
	v_pk_fma_f32 v[64:65], v[112:113], v[8:9], v[64:65]
	v_pk_fma_f32 v[66:67], v[114:115], v[10:11], v[66:67]
	ds_read_b128 v[100:103], v201 offset:46144
	s_waitcnt lgkmcnt(12)
	v_pk_fma_f32 v[64:65], v[116:117], v[12:13], v[64:65]
	v_pk_fma_f32 v[66:67], v[118:119], v[14:15], v[66:67]
	ds_read_b128 v[104:107], v201 offset:46160
	s_waitcnt lgkmcnt(12)
	v_pk_fma_f32 v[64:65], v[120:121], v[16:17], v[64:65]
	v_pk_fma_f32 v[66:67], v[122:123], v[18:19], v[66:67]
	ds_read_b128 v[108:111], v201 offset:46176
	s_waitcnt lgkmcnt(12)
	v_pk_fma_f32 v[64:65], v[124:125], v[20:21], v[64:65]
	v_pk_fma_f32 v[66:67], v[126:127], v[22:23], v[66:67]
	ds_read_b128 v[112:115], v201 offset:46192
	s_waitcnt lgkmcnt(12)
	v_pk_fma_f32 v[64:65], v[128:129], v[24:25], v[64:65]
	v_pk_fma_f32 v[66:67], v[130:131], v[26:27], v[66:67]
	ds_read_b128 v[116:119], v201 offset:46208
	s_waitcnt lgkmcnt(12)
	v_pk_fma_f32 v[64:65], v[132:133], v[28:29], v[64:65]
	v_pk_fma_f32 v[66:67], v[134:135], v[30:31], v[66:67]
	ds_read_b128 v[120:123], v201 offset:46224
	s_waitcnt lgkmcnt(12)
	v_pk_fma_f32 v[64:65], v[136:137], v[32:33], v[64:65]
	v_pk_fma_f32 v[66:67], v[138:139], v[34:35], v[66:67]
	ds_read_b128 v[124:127], v201 offset:46240
	s_waitcnt lgkmcnt(12)
	v_pk_fma_f32 v[64:65], v[140:141], v[36:37], v[64:65]
	v_pk_fma_f32 v[66:67], v[142:143], v[38:39], v[66:67]
	ds_read_b128 v[128:131], v201 offset:46336
	s_waitcnt lgkmcnt(12)
	v_pk_fma_f32 v[64:65], v[144:145], v[40:41], v[64:65]
	v_pk_fma_f32 v[66:67], v[146:147], v[42:43], v[66:67]
	s_nop 0
	v_pk_add_f32 v[68:69], v[64:65], v[66:67]
	s_nop 0
	v_add_f32_e32 v70, v68, v69
	v_sub_f32_e32 v43, v43, v70
	ds_read_b128 v[132:135], v201 offset:46352
	s_waitcnt lgkmcnt(12)
	v_pk_mul_f32 v[64:65], v[148:149], v[0:1]
	v_pk_mul_f32 v[66:67], v[150:151], v[2:3]
	ds_read_b128 v[136:139], v201 offset:46368
	s_waitcnt lgkmcnt(12)
	v_pk_fma_f32 v[64:65], v[152:153], v[4:5], v[64:65]
	v_pk_fma_f32 v[66:67], v[154:155], v[6:7], v[66:67]
	ds_read_b128 v[140:143], v201 offset:46384
	s_waitcnt lgkmcnt(12)
	v_pk_fma_f32 v[64:65], v[156:157], v[8:9], v[64:65]
	v_pk_fma_f32 v[66:67], v[158:159], v[10:11], v[66:67]
	ds_read_b128 v[144:147], v201 offset:46400
	s_waitcnt lgkmcnt(12)
	v_pk_fma_f32 v[64:65], v[96:97], v[12:13], v[64:65]
	v_pk_fma_f32 v[66:67], v[98:99], v[14:15], v[66:67]
	ds_read_b128 v[148:151], v201 offset:46416
	s_waitcnt lgkmcnt(12)
	v_pk_fma_f32 v[64:65], v[100:101], v[16:17], v[64:65]
	v_pk_fma_f32 v[66:67], v[102:103], v[18:19], v[66:67]
	ds_read_b128 v[152:155], v201 offset:46432
	s_waitcnt lgkmcnt(12)
	v_pk_fma_f32 v[64:65], v[104:105], v[20:21], v[64:65]
	v_pk_fma_f32 v[66:67], v[106:107], v[22:23], v[66:67]
	ds_read_b128 v[156:159], v201 offset:46448
	s_waitcnt lgkmcnt(12)
	v_pk_fma_f32 v[64:65], v[108:109], v[24:25], v[64:65]
	v_pk_fma_f32 v[66:67], v[110:111], v[26:27], v[66:67]
	ds_read_b128 v[96:99], v201 offset:46464
	s_waitcnt lgkmcnt(12)
	v_pk_fma_f32 v[64:65], v[112:113], v[28:29], v[64:65]
	v_pk_fma_f32 v[66:67], v[114:115], v[30:31], v[66:67]
	ds_read_b128 v[100:103], v201 offset:46480
	s_waitcnt lgkmcnt(12)
	v_pk_fma_f32 v[64:65], v[116:117], v[32:33], v[64:65]
	v_pk_fma_f32 v[66:67], v[118:119], v[34:35], v[66:67]
	ds_read_b128 v[104:107], v201 offset:46496
	s_waitcnt lgkmcnt(12)
	v_pk_fma_f32 v[64:65], v[120:121], v[36:37], v[64:65]
	v_pk_fma_f32 v[66:67], v[122:123], v[38:39], v[66:67]
	ds_read_b128 v[108:111], v201 offset:46512
	s_waitcnt lgkmcnt(12)
	v_pk_fma_f32 v[64:65], v[124:125], v[40:41], v[64:65]
	v_pk_fma_f32 v[66:67], v[126:127], v[42:43], v[66:67]
	s_nop 0
	v_pk_add_f32 v[68:69], v[64:65], v[66:67]
	s_nop 0
	v_add_f32_e32 v70, v68, v69
	v_sub_f32_e32 v44, v44, v70
	ds_read_b128 v[112:115], v201 offset:46592
	s_waitcnt lgkmcnt(12)
	v_pk_mul_f32 v[64:65], v[128:129], v[0:1]
	v_pk_mul_f32 v[66:67], v[130:131], v[2:3]
	ds_read_b128 v[116:119], v201 offset:46608
	s_waitcnt lgkmcnt(12)
	v_pk_fma_f32 v[64:65], v[132:133], v[4:5], v[64:65]
	v_pk_fma_f32 v[66:67], v[134:135], v[6:7], v[66:67]
	ds_read_b128 v[120:123], v201 offset:46624
	s_waitcnt lgkmcnt(12)
	v_pk_fma_f32 v[64:65], v[136:137], v[8:9], v[64:65]
	v_pk_fma_f32 v[66:67], v[138:139], v[10:11], v[66:67]
	ds_read_b128 v[124:127], v201 offset:46640
	s_waitcnt lgkmcnt(12)
	v_pk_fma_f32 v[64:65], v[140:141], v[12:13], v[64:65]
	v_pk_fma_f32 v[66:67], v[142:143], v[14:15], v[66:67]
	ds_read_b128 v[128:131], v201 offset:46656
	s_waitcnt lgkmcnt(12)
	v_pk_fma_f32 v[64:65], v[144:145], v[16:17], v[64:65]
	v_pk_fma_f32 v[66:67], v[146:147], v[18:19], v[66:67]
	ds_read_b128 v[132:135], v201 offset:46672
	s_waitcnt lgkmcnt(12)
	v_pk_fma_f32 v[64:65], v[148:149], v[20:21], v[64:65]
	v_pk_fma_f32 v[66:67], v[150:151], v[22:23], v[66:67]
	ds_read_b128 v[136:139], v201 offset:46688
	s_waitcnt lgkmcnt(12)
	v_pk_fma_f32 v[64:65], v[152:153], v[24:25], v[64:65]
	v_pk_fma_f32 v[66:67], v[154:155], v[26:27], v[66:67]
	ds_read_b128 v[140:143], v201 offset:46704
	s_waitcnt lgkmcnt(12)
	v_pk_fma_f32 v[64:65], v[156:157], v[28:29], v[64:65]
	v_pk_fma_f32 v[66:67], v[158:159], v[30:31], v[66:67]
	ds_read_b128 v[144:147], v201 offset:46720
	s_waitcnt lgkmcnt(12)
	v_pk_fma_f32 v[64:65], v[96:97], v[32:33], v[64:65]
	v_pk_fma_f32 v[66:67], v[98:99], v[34:35], v[66:67]
	ds_read_b128 v[148:151], v201 offset:46736
	s_waitcnt lgkmcnt(12)
	v_pk_fma_f32 v[64:65], v[100:101], v[36:37], v[64:65]
	v_pk_fma_f32 v[66:67], v[102:103], v[38:39], v[66:67]
	ds_read_b128 v[152:155], v201 offset:46752
	s_waitcnt lgkmcnt(12)
	v_pk_fma_f32 v[64:65], v[104:105], v[40:41], v[64:65]
	v_pk_fma_f32 v[66:67], v[106:107], v[42:43], v[66:67]
	ds_read_b128 v[156:159], v201 offset:46768
	s_waitcnt lgkmcnt(12)
	v_pk_fma_f32 v[64:65], v[108:109], v[44:45], v[64:65]
	v_pk_fma_f32 v[66:67], v[110:111], v[46:47], v[66:67]
	s_nop 0
	v_pk_add_f32 v[68:69], v[64:65], v[66:67]
	s_nop 0
	v_add_f32_e32 v70, v68, v69
	v_sub_f32_e32 v45, v45, v70
	ds_read_b128 v[96:99], v201 offset:46848
	s_waitcnt lgkmcnt(12)
	v_pk_mul_f32 v[64:65], v[112:113], v[0:1]
	v_pk_mul_f32 v[66:67], v[114:115], v[2:3]
	ds_read_b128 v[100:103], v201 offset:46864
	s_waitcnt lgkmcnt(12)
	v_pk_fma_f32 v[64:65], v[116:117], v[4:5], v[64:65]
	v_pk_fma_f32 v[66:67], v[118:119], v[6:7], v[66:67]
	ds_read_b128 v[104:107], v201 offset:46880
	s_waitcnt lgkmcnt(12)
	v_pk_fma_f32 v[64:65], v[120:121], v[8:9], v[64:65]
	v_pk_fma_f32 v[66:67], v[122:123], v[10:11], v[66:67]
	ds_read_b128 v[108:111], v201 offset:46896
	s_waitcnt lgkmcnt(12)
	v_pk_fma_f32 v[64:65], v[124:125], v[12:13], v[64:65]
	v_pk_fma_f32 v[66:67], v[126:127], v[14:15], v[66:67]
	ds_read_b128 v[112:115], v201 offset:46912
	s_waitcnt lgkmcnt(12)
	v_pk_fma_f32 v[64:65], v[128:129], v[16:17], v[64:65]
	v_pk_fma_f32 v[66:67], v[130:131], v[18:19], v[66:67]
	ds_read_b128 v[116:119], v201 offset:46928
	s_waitcnt lgkmcnt(12)
	v_pk_fma_f32 v[64:65], v[132:133], v[20:21], v[64:65]
	v_pk_fma_f32 v[66:67], v[134:135], v[22:23], v[66:67]
	ds_read_b128 v[120:123], v201 offset:46944
	s_waitcnt lgkmcnt(12)
	v_pk_fma_f32 v[64:65], v[136:137], v[24:25], v[64:65]
	v_pk_fma_f32 v[66:67], v[138:139], v[26:27], v[66:67]
	ds_read_b128 v[124:127], v201 offset:46960
	s_waitcnt lgkmcnt(12)
	v_pk_fma_f32 v[64:65], v[140:141], v[28:29], v[64:65]
	v_pk_fma_f32 v[66:67], v[142:143], v[30:31], v[66:67]
	ds_read_b128 v[128:131], v201 offset:46976
	s_waitcnt lgkmcnt(12)
	v_pk_fma_f32 v[64:65], v[144:145], v[32:33], v[64:65]
	v_pk_fma_f32 v[66:67], v[146:147], v[34:35], v[66:67]
	ds_read_b128 v[132:135], v201 offset:46992
	s_waitcnt lgkmcnt(12)
	v_pk_fma_f32 v[64:65], v[148:149], v[36:37], v[64:65]
	v_pk_fma_f32 v[66:67], v[150:151], v[38:39], v[66:67]
	ds_read_b128 v[136:139], v201 offset:47008
	s_waitcnt lgkmcnt(12)
	v_pk_fma_f32 v[64:65], v[152:153], v[40:41], v[64:65]
	v_pk_fma_f32 v[66:67], v[154:155], v[42:43], v[66:67]
	ds_read_b128 v[140:143], v201 offset:47024
	s_waitcnt lgkmcnt(12)
	v_pk_fma_f32 v[64:65], v[156:157], v[44:45], v[64:65]
	v_pk_fma_f32 v[66:67], v[158:159], v[46:47], v[66:67]
	s_nop 0
	v_pk_add_f32 v[68:69], v[64:65], v[66:67]
	s_nop 0
	v_add_f32_e32 v70, v68, v69
	v_sub_f32_e32 v46, v46, v70
	ds_read_b128 v[144:147], v201 offset:47104
	s_waitcnt lgkmcnt(12)
	v_pk_mul_f32 v[64:65], v[96:97], v[0:1]
	v_pk_mul_f32 v[66:67], v[98:99], v[2:3]
	ds_read_b128 v[148:151], v201 offset:47120
	s_waitcnt lgkmcnt(12)
	v_pk_fma_f32 v[64:65], v[100:101], v[4:5], v[64:65]
	v_pk_fma_f32 v[66:67], v[102:103], v[6:7], v[66:67]
	ds_read_b128 v[152:155], v201 offset:47136
	s_waitcnt lgkmcnt(12)
	v_pk_fma_f32 v[64:65], v[104:105], v[8:9], v[64:65]
	v_pk_fma_f32 v[66:67], v[106:107], v[10:11], v[66:67]
	ds_read_b128 v[156:159], v201 offset:47152
	s_waitcnt lgkmcnt(12)
	v_pk_fma_f32 v[64:65], v[108:109], v[12:13], v[64:65]
	v_pk_fma_f32 v[66:67], v[110:111], v[14:15], v[66:67]
	ds_read_b128 v[96:99], v201 offset:47168
	s_waitcnt lgkmcnt(12)
	v_pk_fma_f32 v[64:65], v[112:113], v[16:17], v[64:65]
	v_pk_fma_f32 v[66:67], v[114:115], v[18:19], v[66:67]
	ds_read_b128 v[100:103], v201 offset:47184
	s_waitcnt lgkmcnt(12)
	v_pk_fma_f32 v[64:65], v[116:117], v[20:21], v[64:65]
	v_pk_fma_f32 v[66:67], v[118:119], v[22:23], v[66:67]
	ds_read_b128 v[104:107], v201 offset:47200
	s_waitcnt lgkmcnt(12)
	v_pk_fma_f32 v[64:65], v[120:121], v[24:25], v[64:65]
	v_pk_fma_f32 v[66:67], v[122:123], v[26:27], v[66:67]
	ds_read_b128 v[108:111], v201 offset:47216
	s_waitcnt lgkmcnt(12)
	v_pk_fma_f32 v[64:65], v[124:125], v[28:29], v[64:65]
	v_pk_fma_f32 v[66:67], v[126:127], v[30:31], v[66:67]
	ds_read_b128 v[112:115], v201 offset:47232
	s_waitcnt lgkmcnt(12)
	v_pk_fma_f32 v[64:65], v[128:129], v[32:33], v[64:65]
	v_pk_fma_f32 v[66:67], v[130:131], v[34:35], v[66:67]
	ds_read_b128 v[116:119], v201 offset:47248
	s_waitcnt lgkmcnt(12)
	v_pk_fma_f32 v[64:65], v[132:133], v[36:37], v[64:65]
	v_pk_fma_f32 v[66:67], v[134:135], v[38:39], v[66:67]
	ds_read_b128 v[120:123], v201 offset:47264
	s_waitcnt lgkmcnt(12)
	v_pk_fma_f32 v[64:65], v[136:137], v[40:41], v[64:65]
	v_pk_fma_f32 v[66:67], v[138:139], v[42:43], v[66:67]
	ds_read_b128 v[124:127], v201 offset:47280
	s_waitcnt lgkmcnt(12)
	v_pk_fma_f32 v[64:65], v[140:141], v[44:45], v[64:65]
	v_pk_fma_f32 v[66:67], v[142:143], v[46:47], v[66:67]
	s_nop 0
	v_pk_add_f32 v[68:69], v[64:65], v[66:67]
	s_nop 0
	v_add_f32_e32 v70, v68, v69
	v_sub_f32_e32 v47, v47, v70
	ds_read_b128 v[128:131], v201 offset:47360
	s_waitcnt lgkmcnt(12)
	v_pk_mul_f32 v[64:65], v[144:145], v[0:1]
	v_pk_mul_f32 v[66:67], v[146:147], v[2:3]
	ds_read_b128 v[132:135], v201 offset:47376
	s_waitcnt lgkmcnt(12)
	v_pk_fma_f32 v[64:65], v[148:149], v[4:5], v[64:65]
	v_pk_fma_f32 v[66:67], v[150:151], v[6:7], v[66:67]
	ds_read_b128 v[136:139], v201 offset:47392
	s_waitcnt lgkmcnt(12)
	v_pk_fma_f32 v[64:65], v[152:153], v[8:9], v[64:65]
	v_pk_fma_f32 v[66:67], v[154:155], v[10:11], v[66:67]
	ds_read_b128 v[140:143], v201 offset:47408
	s_waitcnt lgkmcnt(12)
	v_pk_fma_f32 v[64:65], v[156:157], v[12:13], v[64:65]
	v_pk_fma_f32 v[66:67], v[158:159], v[14:15], v[66:67]
	ds_read_b128 v[144:147], v201 offset:47424
	s_waitcnt lgkmcnt(12)
	v_pk_fma_f32 v[64:65], v[96:97], v[16:17], v[64:65]
	v_pk_fma_f32 v[66:67], v[98:99], v[18:19], v[66:67]
	ds_read_b128 v[148:151], v201 offset:47440
	s_waitcnt lgkmcnt(12)
	v_pk_fma_f32 v[64:65], v[100:101], v[20:21], v[64:65]
	v_pk_fma_f32 v[66:67], v[102:103], v[22:23], v[66:67]
	ds_read_b128 v[152:155], v201 offset:47456
	s_waitcnt lgkmcnt(12)
	v_pk_fma_f32 v[64:65], v[104:105], v[24:25], v[64:65]
	v_pk_fma_f32 v[66:67], v[106:107], v[26:27], v[66:67]
	ds_read_b128 v[156:159], v201 offset:47472
	s_waitcnt lgkmcnt(12)
	v_pk_fma_f32 v[64:65], v[108:109], v[28:29], v[64:65]
	v_pk_fma_f32 v[66:67], v[110:111], v[30:31], v[66:67]
	ds_read_b128 v[96:99], v201 offset:47488
	s_waitcnt lgkmcnt(12)
	v_pk_fma_f32 v[64:65], v[112:113], v[32:33], v[64:65]
	v_pk_fma_f32 v[66:67], v[114:115], v[34:35], v[66:67]
	ds_read_b128 v[100:103], v201 offset:47504
	s_waitcnt lgkmcnt(12)
	v_pk_fma_f32 v[64:65], v[116:117], v[36:37], v[64:65]
	v_pk_fma_f32 v[66:67], v[118:119], v[38:39], v[66:67]
	ds_read_b128 v[104:107], v201 offset:47520
	s_waitcnt lgkmcnt(12)
	v_pk_fma_f32 v[64:65], v[120:121], v[40:41], v[64:65]
	v_pk_fma_f32 v[66:67], v[122:123], v[42:43], v[66:67]
	ds_read_b128 v[108:111], v201 offset:47536
	s_waitcnt lgkmcnt(12)
	v_pk_fma_f32 v[64:65], v[124:125], v[44:45], v[64:65]
	v_pk_fma_f32 v[66:67], v[126:127], v[46:47], v[66:67]
	s_nop 0
	v_pk_add_f32 v[68:69], v[64:65], v[66:67]
	s_nop 0
	v_add_f32_e32 v70, v68, v69
	v_sub_f32_e32 v48, v48, v70
	ds_read_b128 v[112:115], v201 offset:47552
	s_waitcnt lgkmcnt(12)
	v_pk_mul_f32 v[64:65], v[128:129], v[0:1]
	v_pk_mul_f32 v[66:67], v[130:131], v[2:3]
	ds_read_b128 v[116:119], v201 offset:47616
	s_waitcnt lgkmcnt(12)
	v_pk_fma_f32 v[64:65], v[132:133], v[4:5], v[64:65]
	v_pk_fma_f32 v[66:67], v[134:135], v[6:7], v[66:67]
	ds_read_b128 v[120:123], v201 offset:47632
	s_waitcnt lgkmcnt(12)
	v_pk_fma_f32 v[64:65], v[136:137], v[8:9], v[64:65]
	v_pk_fma_f32 v[66:67], v[138:139], v[10:11], v[66:67]
	ds_read_b128 v[124:127], v201 offset:47648
	s_waitcnt lgkmcnt(12)
	v_pk_fma_f32 v[64:65], v[140:141], v[12:13], v[64:65]
	v_pk_fma_f32 v[66:67], v[142:143], v[14:15], v[66:67]
	ds_read_b128 v[128:131], v201 offset:47664
	s_waitcnt lgkmcnt(12)
	v_pk_fma_f32 v[64:65], v[144:145], v[16:17], v[64:65]
	v_pk_fma_f32 v[66:67], v[146:147], v[18:19], v[66:67]
	ds_read_b128 v[132:135], v201 offset:47680
	s_waitcnt lgkmcnt(12)
	v_pk_fma_f32 v[64:65], v[148:149], v[20:21], v[64:65]
	v_pk_fma_f32 v[66:67], v[150:151], v[22:23], v[66:67]
	ds_read_b128 v[136:139], v201 offset:47696
	s_waitcnt lgkmcnt(12)
	v_pk_fma_f32 v[64:65], v[152:153], v[24:25], v[64:65]
	v_pk_fma_f32 v[66:67], v[154:155], v[26:27], v[66:67]
	ds_read_b128 v[140:143], v201 offset:47712
	s_waitcnt lgkmcnt(12)
	v_pk_fma_f32 v[64:65], v[156:157], v[28:29], v[64:65]
	v_pk_fma_f32 v[66:67], v[158:159], v[30:31], v[66:67]
	ds_read_b128 v[144:147], v201 offset:47728
	s_waitcnt lgkmcnt(12)
	v_pk_fma_f32 v[64:65], v[96:97], v[32:33], v[64:65]
	v_pk_fma_f32 v[66:67], v[98:99], v[34:35], v[66:67]
	ds_read_b128 v[148:151], v201 offset:47744
	s_waitcnt lgkmcnt(12)
	v_pk_fma_f32 v[64:65], v[100:101], v[36:37], v[64:65]
	v_pk_fma_f32 v[66:67], v[102:103], v[38:39], v[66:67]
	ds_read_b128 v[152:155], v201 offset:47760
	s_waitcnt lgkmcnt(12)
	v_pk_fma_f32 v[64:65], v[104:105], v[40:41], v[64:65]
	v_pk_fma_f32 v[66:67], v[106:107], v[42:43], v[66:67]
	ds_read_b128 v[156:159], v201 offset:47776
	s_waitcnt lgkmcnt(12)
	v_pk_fma_f32 v[64:65], v[108:109], v[44:45], v[64:65]
	v_pk_fma_f32 v[66:67], v[110:111], v[46:47], v[66:67]
	ds_read_b128 v[96:99], v201 offset:47792
	s_waitcnt lgkmcnt(12)
	v_pk_fma_f32 v[64:65], v[112:113], v[48:49], v[64:65]
	v_pk_fma_f32 v[66:67], v[114:115], v[50:51], v[66:67]
	s_nop 0
	v_pk_add_f32 v[68:69], v[64:65], v[66:67]
	s_nop 0
	v_add_f32_e32 v70, v68, v69
	v_sub_f32_e32 v49, v49, v70
	ds_read_b128 v[100:103], v201 offset:47808
	s_waitcnt lgkmcnt(12)
	v_pk_mul_f32 v[64:65], v[116:117], v[0:1]
	v_pk_mul_f32 v[66:67], v[118:119], v[2:3]
	ds_read_b128 v[104:107], v201 offset:47872
	s_waitcnt lgkmcnt(12)
	v_pk_fma_f32 v[64:65], v[120:121], v[4:5], v[64:65]
	v_pk_fma_f32 v[66:67], v[122:123], v[6:7], v[66:67]
	ds_read_b128 v[108:111], v201 offset:47888
	s_waitcnt lgkmcnt(12)
	v_pk_fma_f32 v[64:65], v[124:125], v[8:9], v[64:65]
	v_pk_fma_f32 v[66:67], v[126:127], v[10:11], v[66:67]
	ds_read_b128 v[112:115], v201 offset:47904
	s_waitcnt lgkmcnt(12)
	v_pk_fma_f32 v[64:65], v[128:129], v[12:13], v[64:65]
	v_pk_fma_f32 v[66:67], v[130:131], v[14:15], v[66:67]
	ds_read_b128 v[116:119], v201 offset:47920
	s_waitcnt lgkmcnt(12)
	v_pk_fma_f32 v[64:65], v[132:133], v[16:17], v[64:65]
	v_pk_fma_f32 v[66:67], v[134:135], v[18:19], v[66:67]
	ds_read_b128 v[120:123], v201 offset:47936
	s_waitcnt lgkmcnt(12)
	v_pk_fma_f32 v[64:65], v[136:137], v[20:21], v[64:65]
	v_pk_fma_f32 v[66:67], v[138:139], v[22:23], v[66:67]
	ds_read_b128 v[124:127], v201 offset:47952
	s_waitcnt lgkmcnt(12)
	v_pk_fma_f32 v[64:65], v[140:141], v[24:25], v[64:65]
	v_pk_fma_f32 v[66:67], v[142:143], v[26:27], v[66:67]
	ds_read_b128 v[128:131], v201 offset:47968
	s_waitcnt lgkmcnt(12)
	v_pk_fma_f32 v[64:65], v[144:145], v[28:29], v[64:65]
	v_pk_fma_f32 v[66:67], v[146:147], v[30:31], v[66:67]
	ds_read_b128 v[132:135], v201 offset:47984
	s_waitcnt lgkmcnt(12)
	v_pk_fma_f32 v[64:65], v[148:149], v[32:33], v[64:65]
	v_pk_fma_f32 v[66:67], v[150:151], v[34:35], v[66:67]
	ds_read_b128 v[136:139], v201 offset:48000
	s_waitcnt lgkmcnt(12)
	v_pk_fma_f32 v[64:65], v[152:153], v[36:37], v[64:65]
	v_pk_fma_f32 v[66:67], v[154:155], v[38:39], v[66:67]
	ds_read_b128 v[140:143], v201 offset:48016
	s_waitcnt lgkmcnt(12)
	v_pk_fma_f32 v[64:65], v[156:157], v[40:41], v[64:65]
	v_pk_fma_f32 v[66:67], v[158:159], v[42:43], v[66:67]
	ds_read_b128 v[144:147], v201 offset:48032
	s_waitcnt lgkmcnt(12)
	v_pk_fma_f32 v[64:65], v[96:97], v[44:45], v[64:65]
	v_pk_fma_f32 v[66:67], v[98:99], v[46:47], v[66:67]
	ds_read_b128 v[148:151], v201 offset:48048
	s_waitcnt lgkmcnt(12)
	v_pk_fma_f32 v[64:65], v[100:101], v[48:49], v[64:65]
	v_pk_fma_f32 v[66:67], v[102:103], v[50:51], v[66:67]
	s_nop 0
	v_pk_add_f32 v[68:69], v[64:65], v[66:67]
	s_nop 0
	v_add_f32_e32 v70, v68, v69
	v_sub_f32_e32 v50, v50, v70
	ds_read_b128 v[152:155], v201 offset:48064
	s_waitcnt lgkmcnt(12)
	v_pk_mul_f32 v[64:65], v[104:105], v[0:1]
	v_pk_mul_f32 v[66:67], v[106:107], v[2:3]
	ds_read_b128 v[156:159], v201 offset:48128
	s_waitcnt lgkmcnt(12)
	v_pk_fma_f32 v[64:65], v[108:109], v[4:5], v[64:65]
	v_pk_fma_f32 v[66:67], v[110:111], v[6:7], v[66:67]
	ds_read_b128 v[96:99], v201 offset:48144
	s_waitcnt lgkmcnt(12)
	v_pk_fma_f32 v[64:65], v[112:113], v[8:9], v[64:65]
	v_pk_fma_f32 v[66:67], v[114:115], v[10:11], v[66:67]
	ds_read_b128 v[100:103], v201 offset:48160
	s_waitcnt lgkmcnt(12)
	v_pk_fma_f32 v[64:65], v[116:117], v[12:13], v[64:65]
	v_pk_fma_f32 v[66:67], v[118:119], v[14:15], v[66:67]
	ds_read_b128 v[104:107], v201 offset:48176
	s_waitcnt lgkmcnt(12)
	v_pk_fma_f32 v[64:65], v[120:121], v[16:17], v[64:65]
	v_pk_fma_f32 v[66:67], v[122:123], v[18:19], v[66:67]
	ds_read_b128 v[108:111], v201 offset:48192
	s_waitcnt lgkmcnt(12)
	v_pk_fma_f32 v[64:65], v[124:125], v[20:21], v[64:65]
	v_pk_fma_f32 v[66:67], v[126:127], v[22:23], v[66:67]
	ds_read_b128 v[112:115], v201 offset:48208
	s_waitcnt lgkmcnt(12)
	v_pk_fma_f32 v[64:65], v[128:129], v[24:25], v[64:65]
	v_pk_fma_f32 v[66:67], v[130:131], v[26:27], v[66:67]
	ds_read_b128 v[116:119], v201 offset:48224
	s_waitcnt lgkmcnt(12)
	v_pk_fma_f32 v[64:65], v[132:133], v[28:29], v[64:65]
	v_pk_fma_f32 v[66:67], v[134:135], v[30:31], v[66:67]
	ds_read_b128 v[120:123], v201 offset:48240
	s_waitcnt lgkmcnt(12)
	v_pk_fma_f32 v[64:65], v[136:137], v[32:33], v[64:65]
	v_pk_fma_f32 v[66:67], v[138:139], v[34:35], v[66:67]
	ds_read_b128 v[124:127], v201 offset:48256
	s_waitcnt lgkmcnt(12)
	v_pk_fma_f32 v[64:65], v[140:141], v[36:37], v[64:65]
	v_pk_fma_f32 v[66:67], v[142:143], v[38:39], v[66:67]
	ds_read_b128 v[128:131], v201 offset:48272
	s_waitcnt lgkmcnt(12)
	v_pk_fma_f32 v[64:65], v[144:145], v[40:41], v[64:65]
	v_pk_fma_f32 v[66:67], v[146:147], v[42:43], v[66:67]
	ds_read_b128 v[132:135], v201 offset:48288
	s_waitcnt lgkmcnt(12)
	v_pk_fma_f32 v[64:65], v[148:149], v[44:45], v[64:65]
	v_pk_fma_f32 v[66:67], v[150:151], v[46:47], v[66:67]
	ds_read_b128 v[136:139], v201 offset:48304
	s_waitcnt lgkmcnt(12)
	v_pk_fma_f32 v[64:65], v[152:153], v[48:49], v[64:65]
	v_pk_fma_f32 v[66:67], v[154:155], v[50:51], v[66:67]
	s_nop 0
	v_pk_add_f32 v[68:69], v[64:65], v[66:67]
	s_nop 0
	v_add_f32_e32 v70, v68, v69
	v_sub_f32_e32 v51, v51, v70
	ds_read_b128 v[140:143], v201 offset:48320
	s_waitcnt lgkmcnt(12)
	v_pk_mul_f32 v[64:65], v[156:157], v[0:1]
	v_pk_mul_f32 v[66:67], v[158:159], v[2:3]
	ds_read_b128 v[144:147], v201 offset:48384
	s_waitcnt lgkmcnt(12)
	v_pk_fma_f32 v[64:65], v[96:97], v[4:5], v[64:65]
	v_pk_fma_f32 v[66:67], v[98:99], v[6:7], v[66:67]
	ds_read_b128 v[148:151], v201 offset:48400
	s_waitcnt lgkmcnt(12)
	v_pk_fma_f32 v[64:65], v[100:101], v[8:9], v[64:65]
	v_pk_fma_f32 v[66:67], v[102:103], v[10:11], v[66:67]
	ds_read_b128 v[152:155], v201 offset:48416
	s_waitcnt lgkmcnt(12)
	v_pk_fma_f32 v[64:65], v[104:105], v[12:13], v[64:65]
	v_pk_fma_f32 v[66:67], v[106:107], v[14:15], v[66:67]
	ds_read_b128 v[156:159], v201 offset:48432
	s_waitcnt lgkmcnt(12)
	v_pk_fma_f32 v[64:65], v[108:109], v[16:17], v[64:65]
	v_pk_fma_f32 v[66:67], v[110:111], v[18:19], v[66:67]
	ds_read_b128 v[96:99], v201 offset:48448
	s_waitcnt lgkmcnt(12)
	v_pk_fma_f32 v[64:65], v[112:113], v[20:21], v[64:65]
	v_pk_fma_f32 v[66:67], v[114:115], v[22:23], v[66:67]
	ds_read_b128 v[100:103], v201 offset:48464
	s_waitcnt lgkmcnt(12)
	v_pk_fma_f32 v[64:65], v[116:117], v[24:25], v[64:65]
	v_pk_fma_f32 v[66:67], v[118:119], v[26:27], v[66:67]
	ds_read_b128 v[104:107], v201 offset:48480
	s_waitcnt lgkmcnt(12)
	v_pk_fma_f32 v[64:65], v[120:121], v[28:29], v[64:65]
	v_pk_fma_f32 v[66:67], v[122:123], v[30:31], v[66:67]
	ds_read_b128 v[108:111], v201 offset:48496
	s_waitcnt lgkmcnt(12)
	v_pk_fma_f32 v[64:65], v[124:125], v[32:33], v[64:65]
	v_pk_fma_f32 v[66:67], v[126:127], v[34:35], v[66:67]
	ds_read_b128 v[112:115], v201 offset:48512
	s_waitcnt lgkmcnt(12)
	v_pk_fma_f32 v[64:65], v[128:129], v[36:37], v[64:65]
	v_pk_fma_f32 v[66:67], v[130:131], v[38:39], v[66:67]
	ds_read_b128 v[116:119], v201 offset:48528
	s_waitcnt lgkmcnt(12)
	v_pk_fma_f32 v[64:65], v[132:133], v[40:41], v[64:65]
	v_pk_fma_f32 v[66:67], v[134:135], v[42:43], v[66:67]
	ds_read_b128 v[120:123], v201 offset:48544
	s_waitcnt lgkmcnt(12)
	v_pk_fma_f32 v[64:65], v[136:137], v[44:45], v[64:65]
	v_pk_fma_f32 v[66:67], v[138:139], v[46:47], v[66:67]
	ds_read_b128 v[124:127], v201 offset:48560
	s_waitcnt lgkmcnt(12)
	v_pk_fma_f32 v[64:65], v[140:141], v[48:49], v[64:65]
	v_pk_fma_f32 v[66:67], v[142:143], v[50:51], v[66:67]
	s_nop 0
	v_pk_add_f32 v[68:69], v[64:65], v[66:67]
	s_nop 0
	v_add_f32_e32 v70, v68, v69
	v_sub_f32_e32 v52, v52, v70
	ds_read_b128 v[128:131], v201 offset:48576
	s_waitcnt lgkmcnt(12)
	v_pk_mul_f32 v[64:65], v[144:145], v[0:1]
	v_pk_mul_f32 v[66:67], v[146:147], v[2:3]
	ds_read_b128 v[132:135], v201 offset:48592
	s_waitcnt lgkmcnt(12)
	v_pk_fma_f32 v[64:65], v[148:149], v[4:5], v[64:65]
	v_pk_fma_f32 v[66:67], v[150:151], v[6:7], v[66:67]
	ds_read_b128 v[136:139], v201 offset:48640
	s_waitcnt lgkmcnt(12)
	v_pk_fma_f32 v[64:65], v[152:153], v[8:9], v[64:65]
	v_pk_fma_f32 v[66:67], v[154:155], v[10:11], v[66:67]
	ds_read_b128 v[140:143], v201 offset:48656
	s_waitcnt lgkmcnt(12)
	v_pk_fma_f32 v[64:65], v[156:157], v[12:13], v[64:65]
	v_pk_fma_f32 v[66:67], v[158:159], v[14:15], v[66:67]
	ds_read_b128 v[144:147], v201 offset:48672
	s_waitcnt lgkmcnt(12)
	v_pk_fma_f32 v[64:65], v[96:97], v[16:17], v[64:65]
	v_pk_fma_f32 v[66:67], v[98:99], v[18:19], v[66:67]
	ds_read_b128 v[148:151], v201 offset:48688
	s_waitcnt lgkmcnt(12)
	v_pk_fma_f32 v[64:65], v[100:101], v[20:21], v[64:65]
	v_pk_fma_f32 v[66:67], v[102:103], v[22:23], v[66:67]
	ds_read_b128 v[152:155], v201 offset:48704
	s_waitcnt lgkmcnt(12)
	v_pk_fma_f32 v[64:65], v[104:105], v[24:25], v[64:65]
	v_pk_fma_f32 v[66:67], v[106:107], v[26:27], v[66:67]
	ds_read_b128 v[156:159], v201 offset:48720
	s_waitcnt lgkmcnt(12)
	v_pk_fma_f32 v[64:65], v[108:109], v[28:29], v[64:65]
	v_pk_fma_f32 v[66:67], v[110:111], v[30:31], v[66:67]
	ds_read_b128 v[96:99], v201 offset:48736
	s_waitcnt lgkmcnt(12)
	v_pk_fma_f32 v[64:65], v[112:113], v[32:33], v[64:65]
	v_pk_fma_f32 v[66:67], v[114:115], v[34:35], v[66:67]
	ds_read_b128 v[100:103], v201 offset:48752
	s_waitcnt lgkmcnt(12)
	v_pk_fma_f32 v[64:65], v[116:117], v[36:37], v[64:65]
	v_pk_fma_f32 v[66:67], v[118:119], v[38:39], v[66:67]
	ds_read_b128 v[104:107], v201 offset:48768
	s_waitcnt lgkmcnt(12)
	v_pk_fma_f32 v[64:65], v[120:121], v[40:41], v[64:65]
	v_pk_fma_f32 v[66:67], v[122:123], v[42:43], v[66:67]
	ds_read_b128 v[108:111], v201 offset:48784
	s_waitcnt lgkmcnt(12)
	v_pk_fma_f32 v[64:65], v[124:125], v[44:45], v[64:65]
	v_pk_fma_f32 v[66:67], v[126:127], v[46:47], v[66:67]
	ds_read_b128 v[112:115], v201 offset:48800
	s_waitcnt lgkmcnt(12)
	v_pk_fma_f32 v[64:65], v[128:129], v[48:49], v[64:65]
	v_pk_fma_f32 v[66:67], v[130:131], v[50:51], v[66:67]
	ds_read_b128 v[116:119], v201 offset:48816
	s_waitcnt lgkmcnt(12)
	v_pk_fma_f32 v[64:65], v[132:133], v[52:53], v[64:65]
	v_pk_fma_f32 v[66:67], v[134:135], v[54:55], v[66:67]
	s_nop 0
	v_pk_add_f32 v[68:69], v[64:65], v[66:67]
	s_nop 0
	v_add_f32_e32 v70, v68, v69
	v_sub_f32_e32 v53, v53, v70
	ds_read_b128 v[120:123], v201 offset:48832
	s_waitcnt lgkmcnt(12)
	v_pk_mul_f32 v[64:65], v[136:137], v[0:1]
	v_pk_mul_f32 v[66:67], v[138:139], v[2:3]
	ds_read_b128 v[124:127], v201 offset:48848
	s_waitcnt lgkmcnt(12)
	v_pk_fma_f32 v[64:65], v[140:141], v[4:5], v[64:65]
	v_pk_fma_f32 v[66:67], v[142:143], v[6:7], v[66:67]
	ds_read_b128 v[128:131], v201 offset:48896
	s_waitcnt lgkmcnt(12)
	v_pk_fma_f32 v[64:65], v[144:145], v[8:9], v[64:65]
	v_pk_fma_f32 v[66:67], v[146:147], v[10:11], v[66:67]
	ds_read_b128 v[132:135], v201 offset:48912
	s_waitcnt lgkmcnt(12)
	v_pk_fma_f32 v[64:65], v[148:149], v[12:13], v[64:65]
	v_pk_fma_f32 v[66:67], v[150:151], v[14:15], v[66:67]
	ds_read_b128 v[136:139], v201 offset:48928
	s_waitcnt lgkmcnt(12)
	v_pk_fma_f32 v[64:65], v[152:153], v[16:17], v[64:65]
	v_pk_fma_f32 v[66:67], v[154:155], v[18:19], v[66:67]
	ds_read_b128 v[140:143], v201 offset:48944
	s_waitcnt lgkmcnt(12)
	v_pk_fma_f32 v[64:65], v[156:157], v[20:21], v[64:65]
	v_pk_fma_f32 v[66:67], v[158:159], v[22:23], v[66:67]
	ds_read_b128 v[144:147], v201 offset:48960
	s_waitcnt lgkmcnt(12)
	v_pk_fma_f32 v[64:65], v[96:97], v[24:25], v[64:65]
	v_pk_fma_f32 v[66:67], v[98:99], v[26:27], v[66:67]
	ds_read_b128 v[148:151], v201 offset:48976
	s_waitcnt lgkmcnt(12)
	v_pk_fma_f32 v[64:65], v[100:101], v[28:29], v[64:65]
	v_pk_fma_f32 v[66:67], v[102:103], v[30:31], v[66:67]
	ds_read_b128 v[152:155], v201 offset:48992
	s_waitcnt lgkmcnt(12)
	v_pk_fma_f32 v[64:65], v[104:105], v[32:33], v[64:65]
	v_pk_fma_f32 v[66:67], v[106:107], v[34:35], v[66:67]
	ds_read_b128 v[156:159], v201 offset:49008
	s_waitcnt lgkmcnt(12)
	v_pk_fma_f32 v[64:65], v[108:109], v[36:37], v[64:65]
	v_pk_fma_f32 v[66:67], v[110:111], v[38:39], v[66:67]
	ds_read_b128 v[96:99], v201 offset:49024
	s_waitcnt lgkmcnt(12)
	v_pk_fma_f32 v[64:65], v[112:113], v[40:41], v[64:65]
	v_pk_fma_f32 v[66:67], v[114:115], v[42:43], v[66:67]
	ds_read_b128 v[100:103], v201 offset:49040
	s_waitcnt lgkmcnt(12)
	v_pk_fma_f32 v[64:65], v[116:117], v[44:45], v[64:65]
	v_pk_fma_f32 v[66:67], v[118:119], v[46:47], v[66:67]
	ds_read_b128 v[104:107], v201 offset:49056
	s_waitcnt lgkmcnt(12)
	v_pk_fma_f32 v[64:65], v[120:121], v[48:49], v[64:65]
	v_pk_fma_f32 v[66:67], v[122:123], v[50:51], v[66:67]
	ds_read_b128 v[108:111], v201 offset:49072
	s_waitcnt lgkmcnt(12)
	v_pk_fma_f32 v[64:65], v[124:125], v[52:53], v[64:65]
	v_pk_fma_f32 v[66:67], v[126:127], v[54:55], v[66:67]
	s_nop 0
	v_pk_add_f32 v[68:69], v[64:65], v[66:67]
	s_nop 0
	v_add_f32_e32 v70, v68, v69
	v_sub_f32_e32 v54, v54, v70
	ds_read_b128 v[112:115], v201 offset:49088
	s_waitcnt lgkmcnt(12)
	v_pk_mul_f32 v[64:65], v[128:129], v[0:1]
	v_pk_mul_f32 v[66:67], v[130:131], v[2:3]
	ds_read_b128 v[116:119], v201 offset:49104
	s_waitcnt lgkmcnt(12)
	v_pk_fma_f32 v[64:65], v[132:133], v[4:5], v[64:65]
	v_pk_fma_f32 v[66:67], v[134:135], v[6:7], v[66:67]
	ds_read_b128 v[120:123], v201 offset:49152
	s_waitcnt lgkmcnt(12)
	v_pk_fma_f32 v[64:65], v[136:137], v[8:9], v[64:65]
	v_pk_fma_f32 v[66:67], v[138:139], v[10:11], v[66:67]
	ds_read_b128 v[124:127], v201 offset:49168
	s_waitcnt lgkmcnt(12)
	v_pk_fma_f32 v[64:65], v[140:141], v[12:13], v[64:65]
	v_pk_fma_f32 v[66:67], v[142:143], v[14:15], v[66:67]
	ds_read_b128 v[128:131], v201 offset:49184
	s_waitcnt lgkmcnt(12)
	v_pk_fma_f32 v[64:65], v[144:145], v[16:17], v[64:65]
	v_pk_fma_f32 v[66:67], v[146:147], v[18:19], v[66:67]
	ds_read_b128 v[132:135], v201 offset:49200
	s_waitcnt lgkmcnt(12)
	v_pk_fma_f32 v[64:65], v[148:149], v[20:21], v[64:65]
	v_pk_fma_f32 v[66:67], v[150:151], v[22:23], v[66:67]
	ds_read_b128 v[136:139], v201 offset:49216
	s_waitcnt lgkmcnt(12)
	v_pk_fma_f32 v[64:65], v[152:153], v[24:25], v[64:65]
	v_pk_fma_f32 v[66:67], v[154:155], v[26:27], v[66:67]
	ds_read_b128 v[140:143], v201 offset:49232
	s_waitcnt lgkmcnt(12)
	v_pk_fma_f32 v[64:65], v[156:157], v[28:29], v[64:65]
	v_pk_fma_f32 v[66:67], v[158:159], v[30:31], v[66:67]
	ds_read_b128 v[144:147], v201 offset:49248
	s_waitcnt lgkmcnt(12)
	v_pk_fma_f32 v[64:65], v[96:97], v[32:33], v[64:65]
	v_pk_fma_f32 v[66:67], v[98:99], v[34:35], v[66:67]
	ds_read_b128 v[148:151], v201 offset:49264
	s_waitcnt lgkmcnt(12)
	v_pk_fma_f32 v[64:65], v[100:101], v[36:37], v[64:65]
	v_pk_fma_f32 v[66:67], v[102:103], v[38:39], v[66:67]
	ds_read_b128 v[152:155], v201 offset:49280
	s_waitcnt lgkmcnt(12)
	v_pk_fma_f32 v[64:65], v[104:105], v[40:41], v[64:65]
	v_pk_fma_f32 v[66:67], v[106:107], v[42:43], v[66:67]
	ds_read_b128 v[156:159], v201 offset:49296
	s_waitcnt lgkmcnt(12)
	v_pk_fma_f32 v[64:65], v[108:109], v[44:45], v[64:65]
	v_pk_fma_f32 v[66:67], v[110:111], v[46:47], v[66:67]
	ds_read_b128 v[96:99], v201 offset:49312
	s_waitcnt lgkmcnt(12)
	v_pk_fma_f32 v[64:65], v[112:113], v[48:49], v[64:65]
	v_pk_fma_f32 v[66:67], v[114:115], v[50:51], v[66:67]
	ds_read_b128 v[100:103], v201 offset:49328
	s_waitcnt lgkmcnt(12)
	v_pk_fma_f32 v[64:65], v[116:117], v[52:53], v[64:65]
	v_pk_fma_f32 v[66:67], v[118:119], v[54:55], v[66:67]
	s_nop 0
	v_pk_add_f32 v[68:69], v[64:65], v[66:67]
	s_nop 0
	v_add_f32_e32 v70, v68, v69
	v_sub_f32_e32 v55, v55, v70
	ds_read_b128 v[104:107], v201 offset:49344
	s_waitcnt lgkmcnt(12)
	v_pk_mul_f32 v[64:65], v[120:121], v[0:1]
	v_pk_mul_f32 v[66:67], v[122:123], v[2:3]
	ds_read_b128 v[108:111], v201 offset:49360
	s_waitcnt lgkmcnt(12)
	v_pk_fma_f32 v[64:65], v[124:125], v[4:5], v[64:65]
	v_pk_fma_f32 v[66:67], v[126:127], v[6:7], v[66:67]
	ds_read_b128 v[112:115], v201 offset:49408
	s_waitcnt lgkmcnt(12)
	v_pk_fma_f32 v[64:65], v[128:129], v[8:9], v[64:65]
	v_pk_fma_f32 v[66:67], v[130:131], v[10:11], v[66:67]
	ds_read_b128 v[116:119], v201 offset:49424
	s_waitcnt lgkmcnt(12)
	v_pk_fma_f32 v[64:65], v[132:133], v[12:13], v[64:65]
	v_pk_fma_f32 v[66:67], v[134:135], v[14:15], v[66:67]
	ds_read_b128 v[120:123], v201 offset:49440
	s_waitcnt lgkmcnt(12)
	v_pk_fma_f32 v[64:65], v[136:137], v[16:17], v[64:65]
	v_pk_fma_f32 v[66:67], v[138:139], v[18:19], v[66:67]
	ds_read_b128 v[124:127], v201 offset:49456
	s_waitcnt lgkmcnt(12)
	v_pk_fma_f32 v[64:65], v[140:141], v[20:21], v[64:65]
	v_pk_fma_f32 v[66:67], v[142:143], v[22:23], v[66:67]
	ds_read_b128 v[128:131], v201 offset:49472
	s_waitcnt lgkmcnt(12)
	v_pk_fma_f32 v[64:65], v[144:145], v[24:25], v[64:65]
	v_pk_fma_f32 v[66:67], v[146:147], v[26:27], v[66:67]
	ds_read_b128 v[132:135], v201 offset:49488
	s_waitcnt lgkmcnt(12)
	v_pk_fma_f32 v[64:65], v[148:149], v[28:29], v[64:65]
	v_pk_fma_f32 v[66:67], v[150:151], v[30:31], v[66:67]
	ds_read_b128 v[136:139], v201 offset:49504
	s_waitcnt lgkmcnt(12)
	v_pk_fma_f32 v[64:65], v[152:153], v[32:33], v[64:65]
	v_pk_fma_f32 v[66:67], v[154:155], v[34:35], v[66:67]
	ds_read_b128 v[140:143], v201 offset:49520
	s_waitcnt lgkmcnt(12)
	v_pk_fma_f32 v[64:65], v[156:157], v[36:37], v[64:65]
	v_pk_fma_f32 v[66:67], v[158:159], v[38:39], v[66:67]
	ds_read_b128 v[144:147], v201 offset:49536
	s_waitcnt lgkmcnt(12)
	v_pk_fma_f32 v[64:65], v[96:97], v[40:41], v[64:65]
	v_pk_fma_f32 v[66:67], v[98:99], v[42:43], v[66:67]
	ds_read_b128 v[148:151], v201 offset:49552
	s_waitcnt lgkmcnt(12)
	v_pk_fma_f32 v[64:65], v[100:101], v[44:45], v[64:65]
	v_pk_fma_f32 v[66:67], v[102:103], v[46:47], v[66:67]
	ds_read_b128 v[152:155], v201 offset:49568
	s_waitcnt lgkmcnt(12)
	v_pk_fma_f32 v[64:65], v[104:105], v[48:49], v[64:65]
	v_pk_fma_f32 v[66:67], v[106:107], v[50:51], v[66:67]
	ds_read_b128 v[156:159], v201 offset:49584
	s_waitcnt lgkmcnt(12)
	v_pk_fma_f32 v[64:65], v[108:109], v[52:53], v[64:65]
	v_pk_fma_f32 v[66:67], v[110:111], v[54:55], v[66:67]
	s_nop 0
	v_pk_add_f32 v[68:69], v[64:65], v[66:67]
	s_nop 0
	v_add_f32_e32 v70, v68, v69
	v_sub_f32_e32 v56, v56, v70
	ds_read_b128 v[96:99], v201 offset:49600
	s_waitcnt lgkmcnt(12)
	v_pk_mul_f32 v[64:65], v[112:113], v[0:1]
	v_pk_mul_f32 v[66:67], v[114:115], v[2:3]
	ds_read_b128 v[100:103], v201 offset:49616
	s_waitcnt lgkmcnt(12)
	v_pk_fma_f32 v[64:65], v[116:117], v[4:5], v[64:65]
	v_pk_fma_f32 v[66:67], v[118:119], v[6:7], v[66:67]
	ds_read_b128 v[104:107], v201 offset:49632
	s_waitcnt lgkmcnt(12)
	v_pk_fma_f32 v[64:65], v[120:121], v[8:9], v[64:65]
	v_pk_fma_f32 v[66:67], v[122:123], v[10:11], v[66:67]
	ds_read_b128 v[108:111], v201 offset:49664
	s_waitcnt lgkmcnt(12)
	v_pk_fma_f32 v[64:65], v[124:125], v[12:13], v[64:65]
	v_pk_fma_f32 v[66:67], v[126:127], v[14:15], v[66:67]
	ds_read_b128 v[112:115], v201 offset:49680
	s_waitcnt lgkmcnt(12)
	v_pk_fma_f32 v[64:65], v[128:129], v[16:17], v[64:65]
	v_pk_fma_f32 v[66:67], v[130:131], v[18:19], v[66:67]
	ds_read_b128 v[116:119], v201 offset:49696
	s_waitcnt lgkmcnt(12)
	v_pk_fma_f32 v[64:65], v[132:133], v[20:21], v[64:65]
	v_pk_fma_f32 v[66:67], v[134:135], v[22:23], v[66:67]
	ds_read_b128 v[120:123], v201 offset:49712
	s_waitcnt lgkmcnt(12)
	v_pk_fma_f32 v[64:65], v[136:137], v[24:25], v[64:65]
	v_pk_fma_f32 v[66:67], v[138:139], v[26:27], v[66:67]
	ds_read_b128 v[124:127], v201 offset:49728
	s_waitcnt lgkmcnt(12)
	v_pk_fma_f32 v[64:65], v[140:141], v[28:29], v[64:65]
	v_pk_fma_f32 v[66:67], v[142:143], v[30:31], v[66:67]
	ds_read_b128 v[128:131], v201 offset:49744
	s_waitcnt lgkmcnt(12)
	v_pk_fma_f32 v[64:65], v[144:145], v[32:33], v[64:65]
	v_pk_fma_f32 v[66:67], v[146:147], v[34:35], v[66:67]
	ds_read_b128 v[132:135], v201 offset:49760
	s_waitcnt lgkmcnt(12)
	v_pk_fma_f32 v[64:65], v[148:149], v[36:37], v[64:65]
	v_pk_fma_f32 v[66:67], v[150:151], v[38:39], v[66:67]
	ds_read_b128 v[136:139], v201 offset:49776
	s_waitcnt lgkmcnt(12)
	v_pk_fma_f32 v[64:65], v[152:153], v[40:41], v[64:65]
	v_pk_fma_f32 v[66:67], v[154:155], v[42:43], v[66:67]
	ds_read_b128 v[140:143], v201 offset:49792
	s_waitcnt lgkmcnt(12)
	v_pk_fma_f32 v[64:65], v[156:157], v[44:45], v[64:65]
	v_pk_fma_f32 v[66:67], v[158:159], v[46:47], v[66:67]
	ds_read_b128 v[144:147], v201 offset:49808
	s_waitcnt lgkmcnt(12)
	v_pk_fma_f32 v[64:65], v[96:97], v[48:49], v[64:65]
	v_pk_fma_f32 v[66:67], v[98:99], v[50:51], v[66:67]
	ds_read_b128 v[148:151], v201 offset:49824
	s_waitcnt lgkmcnt(12)
	v_pk_fma_f32 v[64:65], v[100:101], v[52:53], v[64:65]
	v_pk_fma_f32 v[66:67], v[102:103], v[54:55], v[66:67]
	ds_read_b128 v[152:155], v201 offset:49840
	s_waitcnt lgkmcnt(12)
	v_pk_fma_f32 v[64:65], v[104:105], v[56:57], v[64:65]
	v_pk_fma_f32 v[66:67], v[106:107], v[58:59], v[66:67]
	s_nop 0
	v_pk_add_f32 v[68:69], v[64:65], v[66:67]
	s_nop 0
	v_add_f32_e32 v70, v68, v69
	v_sub_f32_e32 v57, v57, v70
	ds_read_b128 v[156:159], v201 offset:49856
	s_waitcnt lgkmcnt(12)
	v_pk_mul_f32 v[64:65], v[108:109], v[0:1]
	v_pk_mul_f32 v[66:67], v[110:111], v[2:3]
	ds_read_b128 v[96:99], v201 offset:49872
	s_waitcnt lgkmcnt(12)
	v_pk_fma_f32 v[64:65], v[112:113], v[4:5], v[64:65]
	v_pk_fma_f32 v[66:67], v[114:115], v[6:7], v[66:67]
	ds_read_b128 v[100:103], v201 offset:49888
	s_waitcnt lgkmcnt(12)
	v_pk_fma_f32 v[64:65], v[116:117], v[8:9], v[64:65]
	v_pk_fma_f32 v[66:67], v[118:119], v[10:11], v[66:67]
	ds_read_b128 v[104:107], v201 offset:49920
	s_waitcnt lgkmcnt(12)
	v_pk_fma_f32 v[64:65], v[120:121], v[12:13], v[64:65]
	v_pk_fma_f32 v[66:67], v[122:123], v[14:15], v[66:67]
	ds_read_b128 v[108:111], v201 offset:49936
	s_waitcnt lgkmcnt(12)
	v_pk_fma_f32 v[64:65], v[124:125], v[16:17], v[64:65]
	v_pk_fma_f32 v[66:67], v[126:127], v[18:19], v[66:67]
	ds_read_b128 v[112:115], v201 offset:49952
	s_waitcnt lgkmcnt(12)
	v_pk_fma_f32 v[64:65], v[128:129], v[20:21], v[64:65]
	v_pk_fma_f32 v[66:67], v[130:131], v[22:23], v[66:67]
	ds_read_b128 v[116:119], v201 offset:49968
	s_waitcnt lgkmcnt(12)
	v_pk_fma_f32 v[64:65], v[132:133], v[24:25], v[64:65]
	v_pk_fma_f32 v[66:67], v[134:135], v[26:27], v[66:67]
	ds_read_b128 v[120:123], v201 offset:49984
	s_waitcnt lgkmcnt(12)
	v_pk_fma_f32 v[64:65], v[136:137], v[28:29], v[64:65]
	v_pk_fma_f32 v[66:67], v[138:139], v[30:31], v[66:67]
	ds_read_b128 v[124:127], v201 offset:50000
	s_waitcnt lgkmcnt(12)
	v_pk_fma_f32 v[64:65], v[140:141], v[32:33], v[64:65]
	v_pk_fma_f32 v[66:67], v[142:143], v[34:35], v[66:67]
	ds_read_b128 v[128:131], v201 offset:50016
	s_waitcnt lgkmcnt(12)
	v_pk_fma_f32 v[64:65], v[144:145], v[36:37], v[64:65]
	v_pk_fma_f32 v[66:67], v[146:147], v[38:39], v[66:67]
	ds_read_b128 v[132:135], v201 offset:50032
	s_waitcnt lgkmcnt(12)
	v_pk_fma_f32 v[64:65], v[148:149], v[40:41], v[64:65]
	v_pk_fma_f32 v[66:67], v[150:151], v[42:43], v[66:67]
	ds_read_b128 v[136:139], v201 offset:50048
	s_waitcnt lgkmcnt(12)
	v_pk_fma_f32 v[64:65], v[152:153], v[44:45], v[64:65]
	v_pk_fma_f32 v[66:67], v[154:155], v[46:47], v[66:67]
	ds_read_b128 v[140:143], v201 offset:50064
	s_waitcnt lgkmcnt(12)
	v_pk_fma_f32 v[64:65], v[156:157], v[48:49], v[64:65]
	v_pk_fma_f32 v[66:67], v[158:159], v[50:51], v[66:67]
	ds_read_b128 v[144:147], v201 offset:50080
	s_waitcnt lgkmcnt(12)
	v_pk_fma_f32 v[64:65], v[96:97], v[52:53], v[64:65]
	v_pk_fma_f32 v[66:67], v[98:99], v[54:55], v[66:67]
	ds_read_b128 v[148:151], v201 offset:50096
	s_waitcnt lgkmcnt(12)
	v_pk_fma_f32 v[64:65], v[100:101], v[56:57], v[64:65]
	v_pk_fma_f32 v[66:67], v[102:103], v[58:59], v[66:67]
	s_nop 0
	v_pk_add_f32 v[68:69], v[64:65], v[66:67]
	s_nop 0
	v_add_f32_e32 v70, v68, v69
	v_sub_f32_e32 v58, v58, v70
	ds_read_b128 v[152:155], v201 offset:50112
	s_waitcnt lgkmcnt(12)
	v_pk_mul_f32 v[64:65], v[104:105], v[0:1]
	v_pk_mul_f32 v[66:67], v[106:107], v[2:3]
	ds_read_b128 v[156:159], v201 offset:50128
	s_waitcnt lgkmcnt(12)
	v_pk_fma_f32 v[64:65], v[108:109], v[4:5], v[64:65]
	v_pk_fma_f32 v[66:67], v[110:111], v[6:7], v[66:67]
	ds_read_b128 v[96:99], v201 offset:50144
	s_waitcnt lgkmcnt(12)
	v_pk_fma_f32 v[64:65], v[112:113], v[8:9], v[64:65]
	v_pk_fma_f32 v[66:67], v[114:115], v[10:11], v[66:67]
	ds_read_b128 v[100:103], v201 offset:50176
	s_waitcnt lgkmcnt(12)
	v_pk_fma_f32 v[64:65], v[116:117], v[12:13], v[64:65]
	v_pk_fma_f32 v[66:67], v[118:119], v[14:15], v[66:67]
	ds_read_b128 v[104:107], v201 offset:50192
	s_waitcnt lgkmcnt(12)
	v_pk_fma_f32 v[64:65], v[120:121], v[16:17], v[64:65]
	v_pk_fma_f32 v[66:67], v[122:123], v[18:19], v[66:67]
	ds_read_b128 v[108:111], v201 offset:50208
	s_waitcnt lgkmcnt(12)
	v_pk_fma_f32 v[64:65], v[124:125], v[20:21], v[64:65]
	v_pk_fma_f32 v[66:67], v[126:127], v[22:23], v[66:67]
	ds_read_b128 v[112:115], v201 offset:50224
	s_waitcnt lgkmcnt(12)
	v_pk_fma_f32 v[64:65], v[128:129], v[24:25], v[64:65]
	v_pk_fma_f32 v[66:67], v[130:131], v[26:27], v[66:67]
	ds_read_b128 v[116:119], v201 offset:50240
	s_waitcnt lgkmcnt(12)
	v_pk_fma_f32 v[64:65], v[132:133], v[28:29], v[64:65]
	v_pk_fma_f32 v[66:67], v[134:135], v[30:31], v[66:67]
	ds_read_b128 v[120:123], v201 offset:50256
	s_waitcnt lgkmcnt(12)
	v_pk_fma_f32 v[64:65], v[136:137], v[32:33], v[64:65]
	v_pk_fma_f32 v[66:67], v[138:139], v[34:35], v[66:67]
	ds_read_b128 v[124:127], v201 offset:50272
	s_waitcnt lgkmcnt(12)
	v_pk_fma_f32 v[64:65], v[140:141], v[36:37], v[64:65]
	v_pk_fma_f32 v[66:67], v[142:143], v[38:39], v[66:67]
	ds_read_b128 v[128:131], v201 offset:50288
	s_waitcnt lgkmcnt(12)
	v_pk_fma_f32 v[64:65], v[144:145], v[40:41], v[64:65]
	v_pk_fma_f32 v[66:67], v[146:147], v[42:43], v[66:67]
	ds_read_b128 v[132:135], v201 offset:50304
	s_waitcnt lgkmcnt(12)
	v_pk_fma_f32 v[64:65], v[148:149], v[44:45], v[64:65]
	v_pk_fma_f32 v[66:67], v[150:151], v[46:47], v[66:67]
	ds_read_b128 v[136:139], v201 offset:50320
	s_waitcnt lgkmcnt(12)
	v_pk_fma_f32 v[64:65], v[152:153], v[48:49], v[64:65]
	v_pk_fma_f32 v[66:67], v[154:155], v[50:51], v[66:67]
	ds_read_b128 v[140:143], v201 offset:50336
	s_waitcnt lgkmcnt(12)
	v_pk_fma_f32 v[64:65], v[156:157], v[52:53], v[64:65]
	v_pk_fma_f32 v[66:67], v[158:159], v[54:55], v[66:67]
	ds_read_b128 v[144:147], v201 offset:50352
	s_waitcnt lgkmcnt(12)
	v_pk_fma_f32 v[64:65], v[96:97], v[56:57], v[64:65]
	v_pk_fma_f32 v[66:67], v[98:99], v[58:59], v[66:67]
	s_nop 0
	v_pk_add_f32 v[68:69], v[64:65], v[66:67]
	s_nop 0
	v_add_f32_e32 v70, v68, v69
	v_sub_f32_e32 v59, v59, v70
	ds_read_b128 v[148:151], v201 offset:50368
	s_waitcnt lgkmcnt(12)
	v_pk_mul_f32 v[64:65], v[100:101], v[0:1]
	v_pk_mul_f32 v[66:67], v[102:103], v[2:3]
	ds_read_b128 v[152:155], v201 offset:50384
	s_waitcnt lgkmcnt(12)
	v_pk_fma_f32 v[64:65], v[104:105], v[4:5], v[64:65]
	v_pk_fma_f32 v[66:67], v[106:107], v[6:7], v[66:67]
	ds_read_b128 v[156:159], v201 offset:50400
	s_waitcnt lgkmcnt(12)
	v_pk_fma_f32 v[64:65], v[108:109], v[8:9], v[64:65]
	v_pk_fma_f32 v[66:67], v[110:111], v[10:11], v[66:67]
	ds_read_b128 v[96:99], v201 offset:50432
	s_waitcnt lgkmcnt(12)
	v_pk_fma_f32 v[64:65], v[112:113], v[12:13], v[64:65]
	v_pk_fma_f32 v[66:67], v[114:115], v[14:15], v[66:67]
	ds_read_b128 v[100:103], v201 offset:50448
	s_waitcnt lgkmcnt(12)
	v_pk_fma_f32 v[64:65], v[116:117], v[16:17], v[64:65]
	v_pk_fma_f32 v[66:67], v[118:119], v[18:19], v[66:67]
	ds_read_b128 v[104:107], v201 offset:50464
	s_waitcnt lgkmcnt(12)
	v_pk_fma_f32 v[64:65], v[120:121], v[20:21], v[64:65]
	v_pk_fma_f32 v[66:67], v[122:123], v[22:23], v[66:67]
	ds_read_b128 v[108:111], v201 offset:50480
	s_waitcnt lgkmcnt(12)
	v_pk_fma_f32 v[64:65], v[124:125], v[24:25], v[64:65]
	v_pk_fma_f32 v[66:67], v[126:127], v[26:27], v[66:67]
	ds_read_b128 v[112:115], v201 offset:50496
	s_waitcnt lgkmcnt(12)
	v_pk_fma_f32 v[64:65], v[128:129], v[28:29], v[64:65]
	v_pk_fma_f32 v[66:67], v[130:131], v[30:31], v[66:67]
	ds_read_b128 v[116:119], v201 offset:50512
	s_waitcnt lgkmcnt(12)
	v_pk_fma_f32 v[64:65], v[132:133], v[32:33], v[64:65]
	v_pk_fma_f32 v[66:67], v[134:135], v[34:35], v[66:67]
	ds_read_b128 v[120:123], v201 offset:50528
	s_waitcnt lgkmcnt(12)
	v_pk_fma_f32 v[64:65], v[136:137], v[36:37], v[64:65]
	v_pk_fma_f32 v[66:67], v[138:139], v[38:39], v[66:67]
	ds_read_b128 v[124:127], v201 offset:50544
	s_waitcnt lgkmcnt(12)
	v_pk_fma_f32 v[64:65], v[140:141], v[40:41], v[64:65]
	v_pk_fma_f32 v[66:67], v[142:143], v[42:43], v[66:67]
	ds_read_b128 v[128:131], v201 offset:50560
	s_waitcnt lgkmcnt(12)
	v_pk_fma_f32 v[64:65], v[144:145], v[44:45], v[64:65]
	v_pk_fma_f32 v[66:67], v[146:147], v[46:47], v[66:67]
	ds_read_b128 v[132:135], v201 offset:50576
	s_waitcnt lgkmcnt(12)
	v_pk_fma_f32 v[64:65], v[148:149], v[48:49], v[64:65]
	v_pk_fma_f32 v[66:67], v[150:151], v[50:51], v[66:67]
	ds_read_b128 v[136:139], v201 offset:50592
	s_waitcnt lgkmcnt(12)
	v_pk_fma_f32 v[64:65], v[152:153], v[52:53], v[64:65]
	v_pk_fma_f32 v[66:67], v[154:155], v[54:55], v[66:67]
	ds_read_b128 v[140:143], v201 offset:50608
	s_waitcnt lgkmcnt(12)
	v_pk_fma_f32 v[64:65], v[156:157], v[56:57], v[64:65]
	v_pk_fma_f32 v[66:67], v[158:159], v[58:59], v[66:67]
	s_nop 0
	v_pk_add_f32 v[68:69], v[64:65], v[66:67]
	s_nop 0
	v_add_f32_e32 v70, v68, v69
	v_sub_f32_e32 v60, v60, v70
	ds_read_b128 v[144:147], v201 offset:50624
	s_waitcnt lgkmcnt(12)
	v_pk_mul_f32 v[64:65], v[96:97], v[0:1]
	v_pk_mul_f32 v[66:67], v[98:99], v[2:3]
	ds_read_b128 v[148:151], v201 offset:50640
	s_waitcnt lgkmcnt(12)
	v_pk_fma_f32 v[64:65], v[100:101], v[4:5], v[64:65]
	v_pk_fma_f32 v[66:67], v[102:103], v[6:7], v[66:67]
	ds_read_b128 v[152:155], v201 offset:50656
	s_waitcnt lgkmcnt(12)
	v_pk_fma_f32 v[64:65], v[104:105], v[8:9], v[64:65]
	v_pk_fma_f32 v[66:67], v[106:107], v[10:11], v[66:67]
	ds_read_b128 v[156:159], v201 offset:50672
	s_waitcnt lgkmcnt(12)
	v_pk_fma_f32 v[64:65], v[108:109], v[12:13], v[64:65]
	v_pk_fma_f32 v[66:67], v[110:111], v[14:15], v[66:67]
	ds_read_b128 v[96:99], v201 offset:50688
	s_waitcnt lgkmcnt(12)
	v_pk_fma_f32 v[64:65], v[112:113], v[16:17], v[64:65]
	v_pk_fma_f32 v[66:67], v[114:115], v[18:19], v[66:67]
	ds_read_b128 v[100:103], v201 offset:50704
	s_waitcnt lgkmcnt(12)
	v_pk_fma_f32 v[64:65], v[116:117], v[20:21], v[64:65]
	v_pk_fma_f32 v[66:67], v[118:119], v[22:23], v[66:67]
	ds_read_b128 v[104:107], v201 offset:50720
	s_waitcnt lgkmcnt(12)
	v_pk_fma_f32 v[64:65], v[120:121], v[24:25], v[64:65]
	v_pk_fma_f32 v[66:67], v[122:123], v[26:27], v[66:67]
	ds_read_b128 v[108:111], v201 offset:50736
	s_waitcnt lgkmcnt(12)
	v_pk_fma_f32 v[64:65], v[124:125], v[28:29], v[64:65]
	v_pk_fma_f32 v[66:67], v[126:127], v[30:31], v[66:67]
	ds_read_b128 v[112:115], v201 offset:50752
	s_waitcnt lgkmcnt(12)
	v_pk_fma_f32 v[64:65], v[128:129], v[32:33], v[64:65]
	v_pk_fma_f32 v[66:67], v[130:131], v[34:35], v[66:67]
	ds_read_b128 v[116:119], v201 offset:50768
	s_waitcnt lgkmcnt(12)
	v_pk_fma_f32 v[64:65], v[132:133], v[36:37], v[64:65]
	v_pk_fma_f32 v[66:67], v[134:135], v[38:39], v[66:67]
	ds_read_b128 v[120:123], v201 offset:50784
	s_waitcnt lgkmcnt(12)
	v_pk_fma_f32 v[64:65], v[136:137], v[40:41], v[64:65]
	v_pk_fma_f32 v[66:67], v[138:139], v[42:43], v[66:67]
	ds_read_b128 v[124:127], v201 offset:50800
	s_waitcnt lgkmcnt(12)
	v_pk_fma_f32 v[64:65], v[140:141], v[44:45], v[64:65]
	v_pk_fma_f32 v[66:67], v[142:143], v[46:47], v[66:67]
	ds_read_b128 v[128:131], v201 offset:50816
	s_waitcnt lgkmcnt(12)
	v_pk_fma_f32 v[64:65], v[144:145], v[48:49], v[64:65]
	v_pk_fma_f32 v[66:67], v[146:147], v[50:51], v[66:67]
	ds_read_b128 v[132:135], v201 offset:50832
	s_waitcnt lgkmcnt(12)
	v_pk_fma_f32 v[64:65], v[148:149], v[52:53], v[64:65]
	v_pk_fma_f32 v[66:67], v[150:151], v[54:55], v[66:67]
	ds_read_b128 v[136:139], v201 offset:50848
	s_waitcnt lgkmcnt(12)
	v_pk_fma_f32 v[64:65], v[152:153], v[56:57], v[64:65]
	v_pk_fma_f32 v[66:67], v[154:155], v[58:59], v[66:67]
	ds_read_b128 v[140:143], v201 offset:50864
	s_waitcnt lgkmcnt(12)
	v_pk_fma_f32 v[64:65], v[156:157], v[60:61], v[64:65]
	v_pk_fma_f32 v[66:67], v[158:159], v[62:63], v[66:67]
	s_nop 0
	v_pk_add_f32 v[68:69], v[64:65], v[66:67]
	s_nop 0
	v_add_f32_e32 v70, v68, v69
	v_sub_f32_e32 v61, v61, v70
	ds_read_b128 v[144:147], v201 offset:50880
	s_waitcnt lgkmcnt(12)
	v_pk_mul_f32 v[64:65], v[96:97], v[0:1]
	v_pk_mul_f32 v[66:67], v[98:99], v[2:3]
	ds_read_b128 v[148:151], v201 offset:50896
	s_waitcnt lgkmcnt(12)
	v_pk_fma_f32 v[64:65], v[100:101], v[4:5], v[64:65]
	v_pk_fma_f32 v[66:67], v[102:103], v[6:7], v[66:67]
	ds_read_b128 v[152:155], v201 offset:50912
	s_waitcnt lgkmcnt(12)
	v_pk_fma_f32 v[64:65], v[104:105], v[8:9], v[64:65]
	v_pk_fma_f32 v[66:67], v[106:107], v[10:11], v[66:67]
	ds_read_b128 v[156:159], v201 offset:50928
	s_waitcnt lgkmcnt(12)
	v_pk_fma_f32 v[64:65], v[108:109], v[12:13], v[64:65]
	v_pk_fma_f32 v[66:67], v[110:111], v[14:15], v[66:67]
	ds_read_b128 v[96:99], v201 offset:50944
	s_waitcnt lgkmcnt(12)
	v_pk_fma_f32 v[64:65], v[112:113], v[16:17], v[64:65]
	v_pk_fma_f32 v[66:67], v[114:115], v[18:19], v[66:67]
	ds_read_b128 v[100:103], v201 offset:50960
	s_waitcnt lgkmcnt(12)
	v_pk_fma_f32 v[64:65], v[116:117], v[20:21], v[64:65]
	v_pk_fma_f32 v[66:67], v[118:119], v[22:23], v[66:67]
	ds_read_b128 v[104:107], v201 offset:50976
	s_waitcnt lgkmcnt(12)
	v_pk_fma_f32 v[64:65], v[120:121], v[24:25], v[64:65]
	v_pk_fma_f32 v[66:67], v[122:123], v[26:27], v[66:67]
	ds_read_b128 v[108:111], v201 offset:50992
	s_waitcnt lgkmcnt(12)
	v_pk_fma_f32 v[64:65], v[124:125], v[28:29], v[64:65]
	v_pk_fma_f32 v[66:67], v[126:127], v[30:31], v[66:67]
	ds_read_b128 v[112:115], v201 offset:51008
	s_waitcnt lgkmcnt(12)
	v_pk_fma_f32 v[64:65], v[128:129], v[32:33], v[64:65]
	v_pk_fma_f32 v[66:67], v[130:131], v[34:35], v[66:67]
	ds_read_b128 v[116:119], v201 offset:51024
	s_waitcnt lgkmcnt(12)
	v_pk_fma_f32 v[64:65], v[132:133], v[36:37], v[64:65]
	v_pk_fma_f32 v[66:67], v[134:135], v[38:39], v[66:67]
	ds_read_b128 v[120:123], v201 offset:51040
	s_waitcnt lgkmcnt(12)
	v_pk_fma_f32 v[64:65], v[136:137], v[40:41], v[64:65]
	v_pk_fma_f32 v[66:67], v[138:139], v[42:43], v[66:67]
	ds_read_b128 v[124:127], v201 offset:51056
	s_waitcnt lgkmcnt(12)
	v_pk_fma_f32 v[64:65], v[140:141], v[44:45], v[64:65]
	v_pk_fma_f32 v[66:67], v[142:143], v[46:47], v[66:67]
	ds_read_b128 v[128:131], v201 offset:51072
	s_waitcnt lgkmcnt(12)
	v_pk_fma_f32 v[64:65], v[144:145], v[48:49], v[64:65]
	v_pk_fma_f32 v[66:67], v[146:147], v[50:51], v[66:67]
	ds_read_b128 v[132:135], v201 offset:51088
	s_waitcnt lgkmcnt(12)
	v_pk_fma_f32 v[64:65], v[148:149], v[52:53], v[64:65]
	v_pk_fma_f32 v[66:67], v[150:151], v[54:55], v[66:67]
	ds_read_b128 v[136:139], v201 offset:51104
	s_waitcnt lgkmcnt(12)
	v_pk_fma_f32 v[64:65], v[152:153], v[56:57], v[64:65]
	v_pk_fma_f32 v[66:67], v[154:155], v[58:59], v[66:67]
	ds_read_b128 v[140:143], v201 offset:51120
	s_waitcnt lgkmcnt(12)
	v_pk_fma_f32 v[64:65], v[156:157], v[60:61], v[64:65]
	v_pk_fma_f32 v[66:67], v[158:159], v[62:63], v[66:67]
	s_nop 0
	v_pk_add_f32 v[68:69], v[64:65], v[66:67]
	s_nop 0
	v_add_f32_e32 v70, v68, v69
	v_sub_f32_e32 v62, v62, v70
	ds_read_b128 v[144:147], v201 offset:51136
	s_waitcnt lgkmcnt(12)
	v_pk_mul_f32 v[64:65], v[96:97], v[0:1]
	v_pk_mul_f32 v[66:67], v[98:99], v[2:3]
	ds_read_b128 v[148:151], v201 offset:51152
	s_waitcnt lgkmcnt(12)
	v_pk_fma_f32 v[64:65], v[100:101], v[4:5], v[64:65]
	v_pk_fma_f32 v[66:67], v[102:103], v[6:7], v[66:67]
	ds_read_b128 v[152:155], v201 offset:51168
	s_waitcnt lgkmcnt(12)
	v_pk_fma_f32 v[64:65], v[104:105], v[8:9], v[64:65]
	v_pk_fma_f32 v[66:67], v[106:107], v[10:11], v[66:67]
	ds_read_b128 v[156:159], v201 offset:51184
	s_waitcnt lgkmcnt(12)
	v_pk_fma_f32 v[64:65], v[108:109], v[12:13], v[64:65]
	v_pk_fma_f32 v[66:67], v[110:111], v[14:15], v[66:67]
	s_waitcnt lgkmcnt(11)
	v_pk_fma_f32 v[64:65], v[112:113], v[16:17], v[64:65]
	v_pk_fma_f32 v[66:67], v[114:115], v[18:19], v[66:67]
	s_waitcnt lgkmcnt(10)
	v_pk_fma_f32 v[64:65], v[116:117], v[20:21], v[64:65]
	v_pk_fma_f32 v[66:67], v[118:119], v[22:23], v[66:67]
	s_waitcnt lgkmcnt(9)
	v_pk_fma_f32 v[64:65], v[120:121], v[24:25], v[64:65]
	v_pk_fma_f32 v[66:67], v[122:123], v[26:27], v[66:67]
	s_waitcnt lgkmcnt(8)
	v_pk_fma_f32 v[64:65], v[124:125], v[28:29], v[64:65]
	v_pk_fma_f32 v[66:67], v[126:127], v[30:31], v[66:67]
	s_waitcnt lgkmcnt(7)
	v_pk_fma_f32 v[64:65], v[128:129], v[32:33], v[64:65]
	v_pk_fma_f32 v[66:67], v[130:131], v[34:35], v[66:67]
	s_waitcnt lgkmcnt(6)
	v_pk_fma_f32 v[64:65], v[132:133], v[36:37], v[64:65]
	v_pk_fma_f32 v[66:67], v[134:135], v[38:39], v[66:67]
	s_waitcnt lgkmcnt(5)
	v_pk_fma_f32 v[64:65], v[136:137], v[40:41], v[64:65]
	v_pk_fma_f32 v[66:67], v[138:139], v[42:43], v[66:67]
	s_waitcnt lgkmcnt(4)
	v_pk_fma_f32 v[64:65], v[140:141], v[44:45], v[64:65]
	v_pk_fma_f32 v[66:67], v[142:143], v[46:47], v[66:67]
	s_waitcnt lgkmcnt(3)
	v_pk_fma_f32 v[64:65], v[144:145], v[48:49], v[64:65]
	v_pk_fma_f32 v[66:67], v[146:147], v[50:51], v[66:67]
	s_waitcnt lgkmcnt(2)
	v_pk_fma_f32 v[64:65], v[148:149], v[52:53], v[64:65]
	v_pk_fma_f32 v[66:67], v[150:151], v[54:55], v[66:67]
	s_waitcnt lgkmcnt(1)
	v_pk_fma_f32 v[64:65], v[152:153], v[56:57], v[64:65]
	v_pk_fma_f32 v[66:67], v[154:155], v[58:59], v[66:67]
	s_waitcnt lgkmcnt(0)
	v_pk_fma_f32 v[64:65], v[156:157], v[60:61], v[64:65]
	v_pk_fma_f32 v[66:67], v[158:159], v[62:63], v[66:67]
	s_nop 0
	v_pk_add_f32 v[68:69], v[64:65], v[66:67]
	s_nop 0
	v_add_f32_e32 v70, v68, v69
	v_sub_f32_e32 v63, v63, v70
	ds_write_b32 v72, v1 offset:272
	ds_write_b32 v72, v2 offset:544
	ds_write_b32 v72, v3 offset:816
	ds_write_b32 v72, v4 offset:1088
	ds_write_b32 v72, v5 offset:1360
	ds_write_b32 v72, v6 offset:1632
	ds_write_b32 v72, v7 offset:1904
	ds_write_b32 v72, v8 offset:2176
	ds_write_b32 v72, v9 offset:2448
	ds_write_b32 v72, v10 offset:2720
	ds_write_b32 v72, v11 offset:2992
	ds_write_b32 v72, v12 offset:3264
	ds_write_b32 v72, v13 offset:3536
	ds_write_b32 v72, v14 offset:3808
	ds_write_b32 v72, v15 offset:4080
	ds_write_b32 v72, v16 offset:4352
	ds_write_b32 v72, v17 offset:4624
	ds_write_b32 v72, v18 offset:4896
	ds_write_b32 v72, v19 offset:5168
	ds_write_b32 v72, v20 offset:5440
	ds_write_b32 v72, v21 offset:5712
	ds_write_b32 v72, v22 offset:5984
	ds_write_b32 v72, v23 offset:6256
	ds_write_b32 v72, v24 offset:6528
	ds_write_b32 v72, v25 offset:6800
	ds_write_b32 v72, v26 offset:7072
	ds_write_b32 v72, v27 offset:7344
	ds_write_b32 v72, v28 offset:7616
	ds_write_b32 v72, v29 offset:7888
	ds_write_b32 v72, v30 offset:8160
	ds_write_b32 v72, v31 offset:8432
	ds_write_b32 v72, v32 offset:8704
	ds_write_b32 v72, v33 offset:8976
	ds_write_b32 v72, v34 offset:9248
	ds_write_b32 v72, v35 offset:9520
	ds_write_b32 v72, v36 offset:9792
	ds_write_b32 v72, v37 offset:10064
	ds_write_b32 v72, v38 offset:10336
	ds_write_b32 v72, v39 offset:10608
	ds_write_b32 v72, v40 offset:10880
	ds_write_b32 v72, v41 offset:11152
	ds_write_b32 v72, v42 offset:11424
	ds_write_b32 v72, v43 offset:11696
	ds_write_b32 v72, v44 offset:11968
	ds_write_b32 v72, v45 offset:12240
	ds_write_b32 v72, v46 offset:12512
	ds_write_b32 v72, v47 offset:12784
	ds_write_b32 v72, v48 offset:13056
	ds_write_b32 v72, v49 offset:13328
	ds_write_b32 v72, v50 offset:13600
	ds_write_b32 v72, v51 offset:13872
	ds_write_b32 v72, v52 offset:14144
	ds_write_b32 v72, v53 offset:14416
	ds_write_b32 v72, v54 offset:14688
	ds_write_b32 v72, v55 offset:14960
	ds_write_b32 v72, v56 offset:15232
	ds_write_b32 v72, v57 offset:15504
	ds_write_b32 v72, v58 offset:15776
	ds_write_b32 v72, v59 offset:16048
	ds_write_b32 v72, v60 offset:16320
	ds_write_b32 v72, v61 offset:16592
	ds_write_b32 v72, v62 offset:16864
	ds_write_b32 v72, v63 offset:17136
.Ldp_fs_end:
.LBB0_421:
	s_waitcnt lgkmcnt(0)
	s_barrier
	s_and_saveexec_b64 s[2:3], s[10:11]
	s_cbranch_execz .LBB0_429
	v_max_i32_e32 v0, 0xf00, v204
	v_sub_u32_e32 v0, v0, v204
	v_add_u32_e32 v1, 0xff, v0
	s_movk_i32 s5, 0xff
	v_cmp_lt_u32_e32 vcc, s5, v1
	s_mov_b64 s[10:11], -1
	v_mov_b32_e32 v0, v204
	s_and_saveexec_b64 s[8:9], vcc
	s_cbranch_execz .LBB0_426
	v_lshrrev_b32_e32 v0, 8, v1
	v_add_u32_e32 v4, 1, v0
	v_and_b32_e32 v5, 0x1fffffe, v4
	v_add_u32_e32 v205, 0x100, v204
	v_mov_b32_e32 v1, v92
	s_mov_b64 s[10:11], 0
	v_mov_b32_e32 v0, v5
	v_mov_b64_e32 v[2:3], v[204:205]
	s_movk_i32 s5, 0x2000
	s_movk_i32 s12, 0x44
